# v27 + trailing half's unit-transition barrier deferred to the K-loop entry (scalar setup of both halves overlaps)
# baseline (speedup 1.0000x reference)
; #define PG8_LAS __attribute__((address_space(3)))
; #define LAS __attribute__((address_space(3)))
;     __host__ __device__ __forceinline__ bool next(int i, Unit& u) const {
;         const long L = (long)i * G + c; if (L >= nwg) return false;
;         int wgid = (int)L; { const int q = nwg / NXCD, r = nwg % NXCD, xcd = wgid % NXCD, off = wgid / NXCD; wgid = (xcd < r ? xcd * (q + 1) : r * (q + 1) + (xcd - r) * q) + off; }
;         const int nig = WGM * nN, gid = wgid / nig, fm = gid * WGM, gsz = (nM - fm) < WGM ? (nM - fm) : WGM;
;         u.pm = fm + ((wgid % nig) % gsz); u.pn = (wgid % nig) / gsz; return true;
; __global__ void __launch_bounds__(NTHREADS, 2) fwd_megakernel(Params p_arg) {
;     ...
;     PG8_LAS unsigned char* lds3 = (PG8_LAS unsigned char*)lds;
;     const KPtr kp0 = (KPtr)__builtin_amdgcn_kernarg_segment_ptr();
;     const int ph_lo = p_arg.ph_lo, ph_hi = p_arg.ph_hi;
;     volatile LAS unsigned* bst = (volatile LAS unsigned*)(lds3 + 163776);
;     if (threadIdx.x < 2) bst[threadIdx.x] = 0u;
;     __syncthreads();
;     XcdBarrier xbar; xbar.bar = nullptr; xbar.x = 0; xbar.st = bst;
;     int ph = 0;
.LBB0_171:
	s_cmpk_lt_i32 s73, 0x680
	s_cselect_b64 s[2:3], -1, 0
	s_ashr_i32 s82, s73, 31
	s_lshr_b32 s1, s82, 29
	s_add_i32 s1, s73, s1
	v_writelane_b32 v254, s4, 3
	s_ashr_i32 s6, s1, 3
	s_and_b32 s1, s1, -8
	v_writelane_b32 v254, s5, 4
	s_sub_i32 s7, s73, s1
	s_ashr_i32 s94, s78, 31
	s_sub_i32 s1, s73, 64
	v_writelane_b32 v254, s2, 5
	s_cmpk_lt_u32 s1, 0x800
	s_mul_i32 s0, s79, s78
	v_writelane_b32 v254, s3, 6
	s_cselect_b64 s[2:3], -1, 0
	v_writelane_b32 v254, s2, 7
	s_lshl_b32 s4, s73, 8
	s_and_b32 s4, s4, 0xf00
	v_writelane_b32 v254, s3, 8
	s_lshl_b32 s2, s1, 4
	s_and_b32 s2, s2, 0x7000
	s_lshl_b32 s1, s1, 2
	s_or_b32 s10, s2, s4
	s_and_b32 s8, s1, 0x3c0
	s_cmpk_lt_i32 s73, 0x840
	s_cselect_b64 s[2:3], -1, 0
	v_writelane_b32 v254, s2, 9
	s_cmpk_lt_i32 s73, 0x800
	s_mov_b32 s75, 0
	v_writelane_b32 v254, s3, 10
	s_cselect_b64 s[2:3], -1, 0
	v_writelane_b32 v254, s2, 11
	s_cmpk_lt_i32 s73, 0x200
	v_lshrrev_b32_e32 v1, 20, v0
	v_writelane_b32 v254, s3, 12
	s_cselect_b64 s[2:3], -1, 0
	s_lshl_b32 s1, s7, 6
	v_writelane_b32 v254, s2, 13
	s_cmpk_lt_i32 s73, 0x400
	v_lshrrev_b32_e32 v0, 10, v0
	v_writelane_b32 v254, s3, 14
	s_cselect_b64 s[2:3], -1, 0
	v_writelane_b32 v254, s2, 15
	s_lshl_b32 s5, s73, 4
	s_and_b32 s4, s73, 7
	v_writelane_b32 v254, s3, 16
	s_lshl_b32 s2, s7, 7
	s_and_b32 s3, s5, 0xffffff80
	s_and_b32 s5, s5, 0xf80
	s_cmp_gt_u32 s4, 3
	s_cselect_b64 s[12:13], -1, 0
	v_writelane_b32 v254, s12, 17
	s_lshl_b32 s4, s4, 7
	v_or_b32_e32 v0, v0, v1
	v_writelane_b32 v254, s13, 18
	v_writelane_b32 v254, s4, 19
	s_sub_i32 s4, 14, s5
	v_writelane_b32 v254, s4, 20
	s_add_i32 s4, s3, -15
	v_writelane_b32 v254, s4, 21
	s_sub_i32 s4, 1, s5
	v_writelane_b32 v254, s4, 22
	v_writelane_b32 v254, s3, 23
	s_add_i32 s3, s3, -2
	s_cmpk_lt_i32 s73, 0xb00
	v_writelane_b32 v254, s3, 24
	s_cselect_b64 s[4:5], -1, 0
	v_writelane_b32 v254, s4, 25
	s_cmp_lt_i32 s7, 0
	s_movk_i32 s3, 0xd1
	v_writelane_b32 v254, s5, 26
	s_load_dword s4, s[86:87], 0xa8
	s_mov_b32 s11, s75
	s_cselect_b32 s5, s3, 0xd0
	v_writelane_b32 v254, s10, 27
	s_mul_i32 s5, s7, s5
	s_waitcnt lgkmcnt(0)
	s_mul_i32 s79, s0, s4
	s_movk_i32 s0, 0x3ff
	v_and_or_b32 v1, v0, s0, v174
	s_mul_i32 s0, s7, 0x41
	s_mul_i32 s4, s7, 0x81
	s_movk_i32 s83, 0x161
	v_writelane_b32 v254, s11, 28
	s_cselect_b32 s9, s0, s1
	s_cselect_b32 s2, s4, s2
	s_cselect_b32 s10, s83, 0x160
	s_add_i32 s5, s5, s6
	s_mul_hi_i32 s0, s5, 0x4ec4ec4f
	s_lshr_b32 s1, s0, 31
	s_ashr_i32 s0, s0, 5
	s_add_i32 s0, s0, s1
	s_mul_i32 s1, s0, 0x68
	s_sub_i32 s1, s5, s1
	s_lshl_b32 s4, s0, 3
	s_bfe_i32 s0, s1, 0x80000
	s_bfe_u32 s0, s0, 0x3000c
	s_add_i32 s5, s1, s0
	s_bfe_i32 s0, s5, 0x80000
	s_and_b32 s5, s5, 0xf8
	s_sub_i32 s1, s1, s5
	s_sext_i32_i16 s11, s0
	s_sext_i32_i8 s1, s1
	s_lshr_b32 s0, s11, 3
	s_add_i32 s12, s4, s1
	s_ashr_i32 s1, s11, 3
	v_writelane_b32 v254, s1, 29
	s_bfe_i64 s[0:1], s[0:1], 0x100000
	s_lshl_b64 s[0:1], s[0:1], 19
	v_writelane_b32 v254, s0, 30
	s_ashr_i32 s13, s12, 31
	s_add_i32 s61, 0, 0x16c00
	v_writelane_b32 v254, s1, 31
	s_add_i32 s0, s9, s6
	s_ashr_i32 s1, s0, 31
	s_lshr_b32 s1, s1, 27
	s_add_i32 s1, s0, s1
	s_ashr_i32 s4, s1, 5
	s_and_b32 s1, s1, 0xffe0
	s_sub_i32 s1, s0, s1
	s_bfe_i32 s0, s1, 0x80000
	s_bfe_u32 s0, s0, 0x3000c
	s_add_i32 s5, s1, s0
	s_bfe_i32 s0, s5, 0x80000
	s_and_b32 s5, s5, 0xf8
	s_sub_i32 s1, s1, s5
	s_lshl_b32 s4, s4, 3
	s_sext_i32_i16 s9, s0
	s_sext_i32_i8 s1, s1
	s_add_i32 s14, s4, s1
	s_ashr_i32 s1, s9, 3
	v_writelane_b32 v254, s1, 32
	s_add_i32 s1, s2, s6
	s_ashr_i32 s2, s1, 31
	s_lshr_b32 s2, s2, 26
	s_add_i32 s2, s1, s2
	s_ashr_i32 s4, s2, 6
	s_and_b32 s2, s2, 0xffc0
	s_sub_i32 s1, s1, s2
	s_bfe_i32 s2, s1, 0x80000
	s_bfe_u32 s2, s2, 0x3000c
	s_add_i32 s5, s1, s2
	s_bfe_i32 s2, s5, 0x80000
	s_and_b32 s5, s5, 0xf8
	s_lshr_b32 s0, s9, 3
	s_sext_i32_i16 s9, s2
	s_sub_i32 s1, s1, s5
	s_lshl_b32 s4, s4, 3
	s_lshr_b32 s2, s9, 3
	s_sext_i32_i8 s1, s1
	s_add_i32 s16, s4, s1
	s_ashr_i32 s1, s9, 3
	s_bfe_i64 s[4:5], s[2:3], 0x100000
	v_writelane_b32 v254, s1, 33
	s_lshl_b64 s[2:3], s[4:5], 19
	s_mul_i32 s1, s7, s10
	v_writelane_b32 v254, s2, 34
	s_add_i32 s1, s1, s6
	s_ashr_i32 s17, s16, 31
	v_writelane_b32 v254, s3, 35
	s_mul_hi_i32 s2, s1, 0x2e8ba2e9
	s_lshr_b32 s4, s2, 31
	s_ashr_i32 s2, s2, 5
	s_add_i32 s2, s2, s4
	s_lshl_b32 s4, s2, 3
	s_mulk_i32 s2, 0xb0
	s_sub_i32 s1, s1, s2
	s_bfe_u32 s2, s1, 0x3001c
	s_add_i32 s5, s1, s2
	s_sext_i32_i16 s6, s5
	s_and_b32 s5, s5, 0xfff8
	s_sub_i32 s1, s1, s5
	s_lshr_b32 s2, s6, 3
	s_sext_i32_i16 s1, s1
	s_add_i32 s10, s4, s1
	s_ashr_i32 s1, s6, 3
	s_bfe_i64 s[4:5], s[2:3], 0x100000
	v_writelane_b32 v254, s1, 36
	s_lshl_b64 s[2:3], s[4:5], 19
	v_writelane_b32 v254, s2, 37
	s_bfe_i64 s[0:1], s[0:1], 0x100000
	s_lshl_b64 s[0:1], s[0:1], 19
	v_writelane_b32 v254, s3, 38
	v_writelane_b32 v254, s0, 39
	s_ashr_i32 s11, s10, 31
	s_ashr_i32 s15, s14, 31
	v_writelane_b32 v254, s1, 40
	s_add_i32 s0, 0, 0x27fc0
	v_writelane_b32 v254, s0, 41
	s_add_i32 s0, 0, 0x27fc4
	v_writelane_b32 v254, s0, 42
	s_lshl_b32 s0, s8, 1
	v_writelane_b32 v254, s0, 43
	s_add_i32 s0, 0, 0x16800
	v_writelane_b32 v254, s0, 44
	s_add_i32 s0, 0, 0x12800
	v_writelane_b32 v254, s0, 45
	s_add_i32 s0, 0, 0x16900
	v_writelane_b32 v254, s0, 46
	s_add_i32 s0, 0, 0x14880
	v_writelane_b32 v254, s0, 47
	s_add_i32 s0, 0, 0x13880
	v_writelane_b32 v254, s0, 48
	v_cmp_eq_u32_e64 s[0:1], 0, v174
	v_mbcnt_lo_u32_b32 v2, -1, 0
	s_mov_b32 s69, 1
	v_writelane_b32 v254, s0, 49
	v_mov_b32_e32 v0, 0
	s_movk_i32 s91, 0x100
	v_writelane_b32 v254, s1, 50
	v_cmp_eq_u32_e64 s[0:1], 0, v1
	v_mov_b32_e32 v175, 0x358637bd
	v_mov_b32_e32 v252, 1
	v_writelane_b32 v254, s0, 51
	v_mov_b32_e32 v253, 0x2000
	s_movk_i32 s59, 0x1ff
	v_writelane_b32 v254, s1, 52
	s_mov_b32 s0, s12
	v_writelane_b32 v254, s0, 53
	s_mov_b32 s93, 0xf149f2ca
	s_mov_b32 s60, 0xf800000
	v_writelane_b32 v254, s1, 54
	s_lshl_b64 s[0:1], s[12:13], 19
	v_writelane_b32 v254, s0, 55
	v_mov_b32_e32 v224, 0x260
	s_movk_i32 s62, 0x110
	v_writelane_b32 v254, s1, 56
	s_mov_b32 s0, s16
	v_writelane_b32 v254, s0, 57
	v_mbcnt_hi_u32_b32 v225, -1, v2
	v_mov_b32_e32 v226, 0xf149f2ca
	v_writelane_b32 v254, s1, 58
	s_lshl_b64 s[0:1], s[16:17], 19
	v_writelane_b32 v254, s0, 59
	v_mov_b32_e32 v227, 0x7f
	v_mov_b64_e32 v[176:177], 0x200
	v_writelane_b32 v254, s1, 60
	s_mov_b32 s0, s10
	v_writelane_b32 v254, s0, 61
	v_mov_b64_e32 v[178:179], 0x1ff
	s_movk_i32 s84, 0x1600
	v_writelane_b32 v254, s1, 62
	s_lshl_b64 s[0:1], s[10:11], 19
	v_writelane_b32 v254, s0, 63
	s_mov_b32 s63, 0
	s_mov_b64 s[96:97], 0x80
	v_writelane_b32 v255, s1, 0
	s_mov_b32 s0, s14
	v_writelane_b32 v255, s0, 1
	s_mov_b64 s[64:65], 0x800
	s_mov_b64 s[66:67], 0x8000
	v_writelane_b32 v255, s1, 2
	s_lshl_b64 s[0:1], s[14:15], 19
	v_writelane_b32 v255, s0, 3
	s_mov_b32 s92, 0xbfb8aa3b
	s_nop 0
	v_writelane_b32 v255, s1, 4
	v_writelane_b32 v255, s61, 5
	v_writelane_b32 v255, s86, 6
	s_nop 1
	v_writelane_b32 v255, s87, 7
	v_writelane_b32 v255, s94, 8
	v_writelane_b32 v255, s82, 9
	s_mov_b32 s101, 0

; template <class Epi, class Sched, bool ALIGN_EPI = false, bool SP2 = false>
; __device__ __forceinline__ void gemm_phase(PG8_LAS unsigned char* lds, const Gemm g, const Sched& S, const Epi& E) {
;     ...
;         const bool has_next = S.next(ui + 1, nxt);
;         const char* nA = has_next ? (const char*)g.A + (size_t)nxt.pm * tstep : cA; const char* nB = has_next ? (const char*)g.Bt + (size_t)nxt.pn * tstep : cB;
;         for (int t = 0; t < nt; t += 2) {
;             const bool last = (t == nt - 2);
;             const char* a1 = cA + (size_t)(t + 1) * kstep;
;             const char* a2 = last ? nA : cA + (size_t)(t + 2) * kstep; const char* b2 = last ? nB : cB + (size_t)(t + 2) * kstep;
;             const char* a3 = a2 + kstep; const char* b3 = b2 + kstep;
;             if (last && has_next) S.a_ready(nxt);
.LBB0_184:
	s_ashr_i32 s23, s22, 31
	s_lshl_b64 s[24:25], s[22:23], 19
	s_add_u32 s24, s2, s24
	s_addc_u32 s25, s36, s25
	s_and_b64 s[26:27], s[8:9], exec
	s_cselect_b32 s23, s25, s29
	s_cselect_b32 s33, s24, s28
	s_ashr_i32 s21, s20, 31
	s_lshl_b64 s[26:27], s[20:21], 19
	s_add_u32 s26, s37, s26
	s_addc_u32 s27, s38, s27
	s_and_b64 s[34:35], s[8:9], exec
	s_cselect_b32 s21, s27, s31
	s_cselect_b32 s51, s26, s30
	s_add_u32 s28, s28, 0x40080
	s_addc_u32 s29, s29, 0
	s_add_u32 s52, s30, 0x100
	s_addc_u32 s53, s31, 0
	s_mov_b32 s54, -2
	s_cmp_eq_u32 s101, 1
	s_cbranch_scc0 .Ldb0
	s_mov_b32 s101, 0
	s_barrier
.Ldb0:
.LBB0_185:
	s_add_u32 s30, s28, 0xfffc0080
	s_addc_u32 s31, s29, -1
	s_add_i32 s55, 0, 0x10000
	s_cmp_eq_u32 s54, 12
	s_cselect_b32 s35, s23, s31
	s_cselect_b32 s34, s33, s30
	v_add_u32_e32 v146, s55, v151
	s_cselect_b32 s31, s21, s53
	s_cselect_b32 s30, s51, s52
	s_add_i32 s58, 0, 0x14000
	s_cmp_lg_u32 s54, 0
	s_cbranch_scc1 .Lodin_nopf
	s_cmp_lt_u32 s39, 0x1000
	s_cbranch_scc0 .Lodin_nopf
	s_lshl_b32 s98, s5, 12
	s_add_u32 s98, s10, s98
	s_addc_u32 s99, s11, 0
	v_lshlrev_b32_e32 v232, 4, v174
	s_add_i32 m0, s39, 0x21000
	s_nop 0
	global_load_lds_dwordx4 v232, s[98:99]

; #define PG8_BAR __builtin_amdgcn_s_barrier()
; template <class Epi, class Sched, bool ALIGN_EPI = false, bool SP2 = false>
; __device__ __forceinline__ void gemm_phase(PG8_LAS unsigned char* lds, const Gemm g, const Sched& S, const Epi& E) {
;     ...
;         if (!has_next) break;
; #pragma unroll
;         for (int a = 0; a < 2; ++a)
; #pragma unroll
;             for (int b = 0; b < 2; ++b)
; #pragma unroll
;                 for (int m = 0; m < 4; ++m)
; #pragma unroll
;                     for (int n = 0; n < 2; ++n) acc[a][b][m][n] = (f32x4){0.f, 0.f, 0.f, 0.f};
;         cur = nxt; cA = nA; cB = nB; ++ui;
;         if constexpr (ALIGN_EPI) { if (wr == 1) PG8_BAR; }
.LBB0_195:
	s_mov_b32 s101, 0
	s_andn2_b64 vcc, exec, s[6:7]
	s_cbranch_vccnz .LBB0_180
	s_mov_b32 s101, 1
	s_branch .LBB0_180

; #define PG8_STAGE(bufoff, gbase, voff) do { _Pragma("unroll") for (int _i = 0; _i < 2; ++_i) \
;         __builtin_amdgcn_global_load_lds((const unsigned*)((const char*)(gbase) + (voff)[_i]), (PG8_LAS unsigned*)(lds + (bufoff) + ldsw + _i * 8192), 16, 0, 0); } while (0)
; #define PG8_LDA(dst, b, h) do { _Pragma("unroll") for (int m = 0; m < 4; ++m) _Pragma("unroll") for (int k = 0; k < 2; ++k) dst[m][k] = *(const PG8_LAS bf16x8*)(lds + PG8_SA(b, h) + aoff + m * 2048 + k * 1024); } while (0)
; #define PG8_LDB(dst, b, h) do { _Pragma("unroll") for (int n = 0; n < 2; ++n) _Pragma("unroll") for (int k = 0; k < 2; ++k) dst[n][k] = *(const PG8_LAS bf16x8*)(lds + PG8_SB(b, h) + boff + n * 2048 + k * 1024); } while (0)
; #define PG8_SCHED __builtin_amdgcn_sched_barrier(0)
; template <class Epi, class Sched, bool ALIGN_EPI = false, bool SP2 = false>
; __device__ __forceinline__ void gemm_phase(PG8_LAS unsigned char* lds, const Gemm g, const Sched& S, const Epi& E) {
;     ...
;         const bool has_next = S.next(ui + 1, nxt);
;         const char* nA = has_next ? (const char*)g.A + (size_t)nxt.pm * tstep : cA; const char* nB = has_next ? (const char*)g.Bt + (size_t)nxt.pn * tstep : cB;
;         for (int t = 0; t < nt; t += 2) {
;             const bool last = (t == nt - 2);
;             const char* a1 = cA + (size_t)(t + 1) * kstep;
;             const char* a2 = last ? nA : cA + (size_t)(t + 2) * kstep; const char* b2 = last ? nB : cB + (size_t)(t + 2) * kstep;
;             const char* a3 = a2 + kstep; const char* b3 = b2 + kstep;
;             if (last && has_next) S.a_ready(nxt);
;             if constexpr (SP2) {
;             PG8_LDB(B0, 0, 0); PG8_LDB(B1, 0, 1); PG8_SCHED; PG8_LDA(At, 0, 0); PG8_STAGE(PG8_SA(1, 1), a1 + hstep, voffA);
;     ...
; #pragma unroll
;         for (int a = 0; a < 2; ++a)
; #pragma unroll
;             for (int b = 0; b < 2; ++b)
; #pragma unroll
;                 for (int m = 0; m < 4; ++m)
; #pragma unroll
;                     for (int n = 0; n < 2; ++n) acc[a][b][m][n] = (f32x4){0.f, 0.f, 0.f, 0.f};
.LBB0_632:
	s_ashr_i32 s29, s28, 31
	s_lshl_b64 s[30:31], s[28:29], 19
	s_add_u32 s30, s38, s30
	s_addc_u32 s31, s39, s31
	s_and_b64 s[34:35], s[8:9], exec
	s_cselect_b32 s5, s31, s11
	s_cselect_b32 s25, s30, s10
	s_ashr_i32 s27, s26, 31
	s_lshl_b64 s[34:35], s[26:27], 19
	s_add_u32 s34, s40, s34
	s_addc_u32 s35, s41, s35
	s_and_b64 s[36:37], s[8:9], exec
	s_cselect_b32 s27, s35, s13
	s_cselect_b32 s29, s34, s12
	s_add_u32 s10, s10, 0x40080
	s_addc_u32 s11, s11, 0
	s_add_u32 s33, s12, 0x100
	s_addc_u32 s54, s13, 0
	s_mov_b32 s55, -2
	s_waitcnt lgkmcnt(0)
	s_cmp_eq_u32 s101, 1
	s_cbranch_scc0 .Ldb3
	s_mov_b32 s101, 0
	s_barrier
.Ldb3:
.LBB0_633:
	s_add_u32 s12, s10, 0xfffc0080
	s_addc_u32 s13, s11, -1
	s_add_i32 s56, 0, 0x10000
	s_cmp_eq_u32 s55, 12
	s_cselect_b32 s37, s5, s13
	s_cselect_b32 s36, s25, s12
	s_cselect_b32 s13, s27, s54
	s_cselect_b32 s12, s29, s33
	s_add_i32 s58, 0, 0x14000
	v_add_u32_e32 v94, s56, v203
	v_add_u32_e32 v134, s58, v203
	ds_read_b128 v[66:69], v94
	ds_read_b128 v[70:73], v94 offset:1024
	ds_read_b128 v[82:85], v94 offset:2048
	ds_read_b128 v[94:97], v94 offset:3072
	ds_read_b128 v[106:109], v134
	ds_read_b128 v[118:121], v134 offset:1024
	ds_read_b128 v[130:133], v134 offset:2048
	ds_read_b128 v[134:137], v134 offset:3072
	v_lshl_add_u64 v[200:201], s[10:11], 0, v[184:185]
	s_add_i32 m0, s43, 0xc000
	ds_read_b128 v[162:165], v204
	ds_read_b128 v[166:169], v204 offset:1024
	ds_read_b128 v[188:191], v204 offset:2048
	ds_read_b128 v[192:195], v204 offset:3072
	ds_read_b128 v[196:199], v204 offset:4096
	ds_read_b128 v[206:209], v204 offset:5120
	ds_read_b128 v[210:213], v204 offset:6144
	ds_read_b128 v[214:217], v204 offset:7168
	global_load_lds_dwordx4 v[200:201], off
	v_lshl_add_u64 v[200:201], s[10:11], 0, v[186:187]
	s_add_i32 m0, s43, 0xe000
	s_nop 0
	global_load_lds_dwordx4 v[200:201], off
	s_cmp_lg_u32 s55, -2
	s_cbranch_scc1 .Lodout_noz
	v_mov_b32_e32 v2, 0
	v_mov_b32_e32 v3, v2
	v_mov_b32_e32 v4, v2
	v_mov_b32_e32 v5, v2
	v_mov_b32_e32 v6, v2
	v_mov_b32_e32 v7, v2
	v_mov_b32_e32 v8, v2
	v_mov_b32_e32 v9, v2
	v_mov_b32_e32 v18, v2
	v_mov_b32_e32 v19, v2
	v_mov_b32_e32 v20, v2
	v_mov_b32_e32 v21, v2
	v_mov_b32_e32 v22, v2
	v_mov_b32_e32 v23, v2
	v_mov_b32_e32 v24, v2
	v_mov_b32_e32 v25, v2
	v_mov_b32_e32 v34, v2
	v_mov_b32_e32 v35, v2
	v_mov_b32_e32 v36, v2
	v_mov_b32_e32 v37, v2
	v_mov_b32_e32 v38, v2
	v_mov_b32_e32 v39, v2
	v_mov_b32_e32 v40, v2
	v_mov_b32_e32 v41, v2
	v_mov_b32_e32 v50, v2
	v_mov_b32_e32 v51, v2
	v_mov_b32_e32 v52, v2
	v_mov_b32_e32 v53, v2
	v_mov_b32_e32 v54, v2
	v_mov_b32_e32 v55, v2
	v_mov_b32_e32 v56, v2
	v_mov_b32_e32 v57, v2
	v_mov_b32_e32 v10, v2
	v_mov_b32_e32 v11, v2
	v_mov_b32_e32 v12, v2
	v_mov_b32_e32 v13, v2
	v_mov_b32_e32 v14, v2
	v_mov_b32_e32 v15, v2
	v_mov_b32_e32 v16, v2
	v_mov_b32_e32 v17, v2
	v_mov_b32_e32 v26, v2
	v_mov_b32_e32 v27, v2
	v_mov_b32_e32 v28, v2
	v_mov_b32_e32 v29, v2
	v_mov_b32_e32 v30, v2
	v_mov_b32_e32 v31, v2
	v_mov_b32_e32 v32, v2
	v_mov_b32_e32 v33, v2
	v_mov_b32_e32 v42, v2
	v_mov_b32_e32 v43, v2
	v_mov_b32_e32 v44, v2
	v_mov_b32_e32 v45, v2
	v_mov_b32_e32 v46, v2
	v_mov_b32_e32 v47, v2
	v_mov_b32_e32 v48, v2
	v_mov_b32_e32 v49, v2
	v_mov_b32_e32 v58, v2
	v_mov_b32_e32 v59, v2
	v_mov_b32_e32 v60, v2
	v_mov_b32_e32 v61, v2
	v_mov_b32_e32 v62, v2
	v_mov_b32_e32 v63, v2
	v_mov_b32_e32 v64, v2
	v_mov_b32_e32 v65, v2
	v_mov_b32_e32 v74, v2
	v_mov_b32_e32 v75, v2
	v_mov_b32_e32 v76, v2
	v_mov_b32_e32 v77, v2
	v_mov_b32_e32 v78, v2
	v_mov_b32_e32 v79, v2
	v_mov_b32_e32 v80, v2
	v_mov_b32_e32 v81, v2
	v_mov_b32_e32 v98, v2
	v_mov_b32_e32 v99, v2
	v_mov_b32_e32 v100, v2
	v_mov_b32_e32 v101, v2
	v_mov_b32_e32 v102, v2
	v_mov_b32_e32 v103, v2
	v_mov_b32_e32 v104, v2
	v_mov_b32_e32 v105, v2
	v_mov_b32_e32 v122, v2
	v_mov_b32_e32 v123, v2
	v_mov_b32_e32 v124, v2
	v_mov_b32_e32 v125, v2
	v_mov_b32_e32 v126, v2
	v_mov_b32_e32 v127, v2
	v_mov_b32_e32 v128, v2
	v_mov_b32_e32 v129, v2
	v_mov_b32_e32 v146, v2
	v_mov_b32_e32 v147, v2
	v_mov_b32_e32 v148, v2
	v_mov_b32_e32 v149, v2
	v_mov_b32_e32 v150, v2
	v_mov_b32_e32 v151, v2
	v_mov_b32_e32 v152, v2
	v_mov_b32_e32 v153, v2
	v_mov_b32_e32 v86, v2
	v_mov_b32_e32 v87, v2
	v_mov_b32_e32 v88, v2
	v_mov_b32_e32 v89, v2
	v_mov_b32_e32 v90, v2
	v_mov_b32_e32 v91, v2
	v_mov_b32_e32 v92, v2
	v_mov_b32_e32 v93, v2
	v_mov_b32_e32 v110, v2
	v_mov_b32_e32 v111, v2
	v_mov_b32_e32 v112, v2
	v_mov_b32_e32 v113, v2
	v_mov_b32_e32 v114, v2
	v_mov_b32_e32 v115, v2
	v_mov_b32_e32 v116, v2
	v_mov_b32_e32 v117, v2
	v_mov_b32_e32 v138, v2
	v_mov_b32_e32 v139, v2
	v_mov_b32_e32 v140, v2
	v_mov_b32_e32 v141, v2
	v_mov_b32_e32 v142, v2
	v_mov_b32_e32 v143, v2
	v_mov_b32_e32 v144, v2
	v_mov_b32_e32 v145, v2
	v_mov_b32_e32 v154, v2
	v_mov_b32_e32 v155, v2
	v_mov_b32_e32 v156, v2
	v_mov_b32_e32 v157, v2
	v_mov_b32_e32 v158, v2
	v_mov_b32_e32 v159, v2
	v_mov_b32_e32 v160, v2
	v_mov_b32_e32 v161, v2

; #define PG8_BAR __builtin_amdgcn_s_barrier()
; template <class Epi, class Sched, bool ALIGN_EPI = false, bool SP2 = false>
; __device__ __forceinline__ void gemm_phase(PG8_LAS unsigned char* lds, const Gemm g, const Sched& S, const Epi& E) {
;     ...
;         if constexpr (!Epi::AFTER_DRAIN) { E(acc, cur, wr, wc, fr, fq); S.done(cur); }
;         if (!has_next) break;
; #pragma unroll
;         for (int a = 0; a < 2; ++a)
; #pragma unroll
;             for (int b = 0; b < 2; ++b)
; #pragma unroll
;                 for (int m = 0; m < 4; ++m)
; #pragma unroll
;                     for (int n = 0; n < 2; ++n) acc[a][b][m][n] = (f32x4){0.f, 0.f, 0.f, 0.f};
;         cur = nxt; cA = nA; cB = nB; ++ui;
;         if constexpr (ALIGN_EPI) { if (wr == 1) PG8_BAR; }
.LBB0_710:
	s_or_b64 exec, exec, s[10:11]
	s_andn2_b64 vcc, exec, s[8:9]
	s_mov_b64 s[8:9], -1
	s_cbranch_vccnz .LBB0_625
	s_mov_b32 s101, 0
	s_andn2_b64 vcc, exec, s[6:7]
	s_cbranch_vccnz .LBB0_624
	s_mov_b32 s101, 1
	s_branch .LBB0_624

; template <class Epi, class Sched, bool ALIGN_EPI = false, bool SP2 = false>
; __device__ __forceinline__ void gemm_phase(PG8_LAS unsigned char* lds, const Gemm g, const Sched& S, const Epi& E) {
;     ...
;         const bool has_next = S.next(ui + 1, nxt);
;         const char* nA = has_next ? (const char*)g.A + (size_t)nxt.pm * tstep : cA; const char* nB = has_next ? (const char*)g.Bt + (size_t)nxt.pn * tstep : cB;
;         for (int t = 0; t < nt; t += 2) {
;             const bool last = (t == nt - 2);
;             const char* a1 = cA + (size_t)(t + 1) * kstep;
;             const char* a2 = last ? nA : cA + (size_t)(t + 2) * kstep; const char* b2 = last ? nB : cB + (size_t)(t + 2) * kstep;
;             const char* a3 = a2 + kstep; const char* b3 = b2 + kstep;
;             if (last && has_next) S.a_ready(nxt);
.LBB0_811:
	s_ashr_i32 s19, s18, 31
	s_lshl_b64 s[20:21], s[18:19], 19
	s_add_u32 s20, s2, s20
	s_addc_u32 s21, s30, s21
	s_and_b64 s[22:23], s[6:7], exec
	s_cselect_b32 s19, s21, s25
	s_cselect_b32 s33, s20, s24
	s_ashr_i32 s17, s16, 31
	s_lshl_b64 s[22:23], s[16:17], 19
	s_add_u32 s22, s31, s22
	s_addc_u32 s23, s34, s23
	s_and_b64 s[28:29], s[6:7], exec
	s_cselect_b32 s17, s23, s27
	s_cselect_b32 s45, s22, s26
	s_add_u32 s24, s24, 0x40080
	s_addc_u32 s25, s25, 0
	s_add_u32 s46, s26, 0x100
	s_addc_u32 s47, s27, 0
	s_mov_b32 s48, -2
	s_cmp_eq_u32 s101, 1
	s_cbranch_scc0 .Ldb1
	s_mov_b32 s101, 0
	s_barrier
.Ldb1:
.LBB0_812:
	s_add_u32 s26, s24, 0xfffc0080
	s_addc_u32 s27, s25, -1
	s_add_i32 s49, 0, 0x10000
	s_cmp_eq_u32 s48, 12
	s_cselect_b32 s29, s19, s27
	s_cselect_b32 s28, s33, s26
	v_add_u32_e32 v142, s49, v145
	s_cselect_b32 s27, s17, s47
	s_cselect_b32 s26, s45, s46
	s_add_i32 s52, 0, 0x14000
	s_cmp_lg_u32 s48, 0
	s_cbranch_scc1 .Levin_nopf
	s_cmp_lt_u32 s35, 0x1000
	s_cbranch_scc0 .Levin_nopf
	s_lshl_b32 s98, s5, 12
	s_add_u32 s98, s10, s98
	s_addc_u32 s99, s11, 0
	v_lshlrev_b32_e32 v232, 4, v174
	s_add_i32 m0, s35, 0x21000
	s_nop 0
	global_load_lds_dwordx4 v232, s[98:99]

; #define PG8_BAR __builtin_amdgcn_s_barrier()
; template <class Epi, class Sched, bool ALIGN_EPI = false, bool SP2 = false>
; __device__ __forceinline__ void gemm_phase(PG8_LAS unsigned char* lds, const Gemm g, const Sched& S, const Epi& E) {
;     ...
;         if (!has_next) break;
; #pragma unroll
;         for (int a = 0; a < 2; ++a)
; #pragma unroll
;             for (int b = 0; b < 2; ++b)
; #pragma unroll
;                 for (int m = 0; m < 4; ++m)
; #pragma unroll
;                     for (int n = 0; n < 2; ++n) acc[a][b][m][n] = (f32x4){0.f, 0.f, 0.f, 0.f};
;         cur = nxt; cA = nA; cB = nB; ++ui;
;         if constexpr (ALIGN_EPI) { if (wr == 1) PG8_BAR; }
.LBB0_817:
	s_andn2_b64 vcc, exec, s[6:7]
	s_mov_b64 s[6:7], -1
	s_cbranch_vccnz .LBB0_804
	s_mov_b32 s101, 0
	s_andn2_b64 vcc, exec, s[8:9]
	s_cbranch_vccnz .LBB0_803
	s_mov_b32 s101, 1
	s_branch .LBB0_803

; #define PG8_STAGE(bufoff, gbase, voff) do { _Pragma("unroll") for (int _i = 0; _i < 2; ++_i) \
;         __builtin_amdgcn_global_load_lds((const unsigned*)((const char*)(gbase) + (voff)[_i]), (PG8_LAS unsigned*)(lds + (bufoff) + ldsw + _i * 8192), 16, 0, 0); } while (0)
; #define PG8_LDA(dst, b, h) do { _Pragma("unroll") for (int m = 0; m < 4; ++m) _Pragma("unroll") for (int k = 0; k < 2; ++k) dst[m][k] = *(const PG8_LAS bf16x8*)(lds + PG8_SA(b, h) + aoff + m * 2048 + k * 1024); } while (0)
; #define PG8_LDB(dst, b, h) do { _Pragma("unroll") for (int n = 0; n < 2; ++n) _Pragma("unroll") for (int k = 0; k < 2; ++k) dst[n][k] = *(const PG8_LAS bf16x8*)(lds + PG8_SB(b, h) + boff + n * 2048 + k * 1024); } while (0)
; #define PG8_SCHED __builtin_amdgcn_sched_barrier(0)
; template <class Epi, class Sched, bool ALIGN_EPI = false, bool SP2 = false>
; __device__ __forceinline__ void gemm_phase(PG8_LAS unsigned char* lds, const Gemm g, const Sched& S, const Epi& E) {
;     ...
;         const bool has_next = S.next(ui + 1, nxt);
;         const char* nA = has_next ? (const char*)g.A + (size_t)nxt.pm * tstep : cA; const char* nB = has_next ? (const char*)g.Bt + (size_t)nxt.pn * tstep : cB;
;         for (int t = 0; t < nt; t += 2) {
;             const bool last = (t == nt - 2);
;             const char* a1 = cA + (size_t)(t + 1) * kstep;
;             const char* a2 = last ? nA : cA + (size_t)(t + 2) * kstep; const char* b2 = last ? nB : cB + (size_t)(t + 2) * kstep;
;             const char* a3 = a2 + kstep; const char* b3 = b2 + kstep;
;             if (last && has_next) S.a_ready(nxt);
;             if constexpr (SP2) {
;             PG8_LDB(B0, 0, 0); PG8_LDB(B1, 0, 1); PG8_SCHED; PG8_LDA(At, 0, 0); PG8_STAGE(PG8_SA(1, 1), a1 + hstep, voffA);
;     ...
; #pragma unroll
;         for (int a = 0; a < 2; ++a)
; #pragma unroll
;             for (int b = 0; b < 2; ++b)
; #pragma unroll
;                 for (int m = 0; m < 4; ++m)
; #pragma unroll
;                     for (int n = 0; n < 2; ++n) acc[a][b][m][n] = (f32x4){0.f, 0.f, 0.f, 0.f};
.LBB0_1074:
	s_ashr_i32 s29, s28, 31
	s_lshl_b64 s[30:31], s[28:29], 19
	s_add_u32 s30, s2, s30
	s_addc_u32 s31, s39, s31
	s_and_b64 s[34:35], s[6:7], exec
	s_cselect_b32 s5, s31, s9
	s_cselect_b32 s25, s30, s8
	s_ashr_i32 s27, s26, 31
	s_lshl_b64 s[34:35], s[26:27], 19
	s_add_u32 s34, s40, s34
	s_addc_u32 s35, s41, s35
	s_and_b64 s[36:37], s[6:7], exec
	s_cselect_b32 s27, s35, s11
	s_cselect_b32 s29, s34, s10
	s_add_u32 s8, s8, 0x40080
	s_addc_u32 s9, s9, 0
	s_add_u32 s33, s10, 0x100
	s_addc_u32 s54, s11, 0
	s_mov_b32 s55, -2
	s_waitcnt lgkmcnt(0)
	s_cmp_eq_u32 s101, 1
	s_cbranch_scc0 .Ldb4
	s_mov_b32 s101, 0
	s_barrier
.Ldb4:
.LBB0_1075:
	s_add_u32 s10, s8, 0xfffc0080
	s_addc_u32 s11, s9, -1
	s_add_i32 s56, 0, 0x10000
	s_cmp_eq_u32 s55, 12
	s_cselect_b32 s37, s5, s11
	s_cselect_b32 s36, s25, s10
	s_cselect_b32 s11, s27, s54
	s_cselect_b32 s10, s29, s33
	s_add_i32 s58, 0, 0x14000
	v_add_u32_e32 v94, s56, v203
	v_add_u32_e32 v134, s58, v203
	ds_read_b128 v[66:69], v94
	ds_read_b128 v[70:73], v94 offset:1024
	ds_read_b128 v[82:85], v94 offset:2048
	ds_read_b128 v[94:97], v94 offset:3072
	ds_read_b128 v[106:109], v134
	ds_read_b128 v[118:121], v134 offset:1024
	ds_read_b128 v[130:133], v134 offset:2048
	ds_read_b128 v[134:137], v134 offset:3072
	v_lshl_add_u64 v[200:201], s[8:9], 0, v[184:185]
	s_add_i32 m0, s43, 0xc000
	ds_read_b128 v[162:165], v204
	ds_read_b128 v[166:169], v204 offset:1024
	ds_read_b128 v[188:191], v204 offset:2048
	ds_read_b128 v[192:195], v204 offset:3072
	ds_read_b128 v[196:199], v204 offset:4096
	ds_read_b128 v[206:209], v204 offset:5120
	ds_read_b128 v[210:213], v204 offset:6144
	ds_read_b128 v[214:217], v204 offset:7168
	global_load_lds_dwordx4 v[200:201], off
	v_lshl_add_u64 v[200:201], s[8:9], 0, v[186:187]
	s_add_i32 m0, s43, 0xe000
	s_nop 0
	global_load_lds_dwordx4 v[200:201], off
	s_cmp_lg_u32 s55, -2
	s_cbranch_scc1 .Levout_noz
	v_mov_b32_e32 v2, 0
	v_mov_b32_e32 v3, v2
	v_mov_b32_e32 v4, v2
	v_mov_b32_e32 v5, v2
	v_mov_b32_e32 v6, v2
	v_mov_b32_e32 v7, v2
	v_mov_b32_e32 v8, v2
	v_mov_b32_e32 v9, v2
	v_mov_b32_e32 v18, v2
	v_mov_b32_e32 v19, v2
	v_mov_b32_e32 v20, v2
	v_mov_b32_e32 v21, v2
	v_mov_b32_e32 v22, v2
	v_mov_b32_e32 v23, v2
	v_mov_b32_e32 v24, v2
	v_mov_b32_e32 v25, v2
	v_mov_b32_e32 v34, v2
	v_mov_b32_e32 v35, v2
	v_mov_b32_e32 v36, v2
	v_mov_b32_e32 v37, v2
	v_mov_b32_e32 v38, v2
	v_mov_b32_e32 v39, v2
	v_mov_b32_e32 v40, v2
	v_mov_b32_e32 v41, v2
	v_mov_b32_e32 v50, v2
	v_mov_b32_e32 v51, v2
	v_mov_b32_e32 v52, v2
	v_mov_b32_e32 v53, v2
	v_mov_b32_e32 v54, v2
	v_mov_b32_e32 v55, v2
	v_mov_b32_e32 v56, v2
	v_mov_b32_e32 v57, v2
	v_mov_b32_e32 v10, v2
	v_mov_b32_e32 v11, v2
	v_mov_b32_e32 v12, v2
	v_mov_b32_e32 v13, v2
	v_mov_b32_e32 v14, v2
	v_mov_b32_e32 v15, v2
	v_mov_b32_e32 v16, v2
	v_mov_b32_e32 v17, v2
	v_mov_b32_e32 v26, v2
	v_mov_b32_e32 v27, v2
	v_mov_b32_e32 v28, v2
	v_mov_b32_e32 v29, v2
	v_mov_b32_e32 v30, v2
	v_mov_b32_e32 v31, v2
	v_mov_b32_e32 v32, v2
	v_mov_b32_e32 v33, v2
	v_mov_b32_e32 v42, v2
	v_mov_b32_e32 v43, v2
	v_mov_b32_e32 v44, v2
	v_mov_b32_e32 v45, v2
	v_mov_b32_e32 v46, v2
	v_mov_b32_e32 v47, v2
	v_mov_b32_e32 v48, v2
	v_mov_b32_e32 v49, v2
	v_mov_b32_e32 v58, v2
	v_mov_b32_e32 v59, v2
	v_mov_b32_e32 v60, v2
	v_mov_b32_e32 v61, v2
	v_mov_b32_e32 v62, v2
	v_mov_b32_e32 v63, v2
	v_mov_b32_e32 v64, v2
	v_mov_b32_e32 v65, v2
	v_mov_b32_e32 v74, v2
	v_mov_b32_e32 v75, v2
	v_mov_b32_e32 v76, v2
	v_mov_b32_e32 v77, v2
	v_mov_b32_e32 v78, v2
	v_mov_b32_e32 v79, v2
	v_mov_b32_e32 v80, v2
	v_mov_b32_e32 v81, v2
	v_mov_b32_e32 v98, v2
	v_mov_b32_e32 v99, v2
	v_mov_b32_e32 v100, v2
	v_mov_b32_e32 v101, v2
	v_mov_b32_e32 v102, v2
	v_mov_b32_e32 v103, v2
	v_mov_b32_e32 v104, v2
	v_mov_b32_e32 v105, v2
	v_mov_b32_e32 v122, v2
	v_mov_b32_e32 v123, v2
	v_mov_b32_e32 v124, v2
	v_mov_b32_e32 v125, v2
	v_mov_b32_e32 v126, v2
	v_mov_b32_e32 v127, v2
	v_mov_b32_e32 v128, v2
	v_mov_b32_e32 v129, v2
	v_mov_b32_e32 v146, v2
	v_mov_b32_e32 v147, v2
	v_mov_b32_e32 v148, v2
	v_mov_b32_e32 v149, v2
	v_mov_b32_e32 v150, v2
	v_mov_b32_e32 v151, v2
	v_mov_b32_e32 v152, v2
	v_mov_b32_e32 v153, v2
	v_mov_b32_e32 v86, v2
	v_mov_b32_e32 v87, v2
	v_mov_b32_e32 v88, v2
	v_mov_b32_e32 v89, v2
	v_mov_b32_e32 v90, v2
	v_mov_b32_e32 v91, v2
	v_mov_b32_e32 v92, v2
	v_mov_b32_e32 v93, v2
	v_mov_b32_e32 v110, v2
	v_mov_b32_e32 v111, v2
	v_mov_b32_e32 v112, v2
	v_mov_b32_e32 v113, v2
	v_mov_b32_e32 v114, v2
	v_mov_b32_e32 v115, v2
	v_mov_b32_e32 v116, v2
	v_mov_b32_e32 v117, v2
	v_mov_b32_e32 v138, v2
	v_mov_b32_e32 v139, v2
	v_mov_b32_e32 v140, v2
	v_mov_b32_e32 v141, v2
	v_mov_b32_e32 v142, v2
	v_mov_b32_e32 v143, v2
	v_mov_b32_e32 v144, v2
	v_mov_b32_e32 v145, v2
	v_mov_b32_e32 v154, v2
	v_mov_b32_e32 v155, v2
	v_mov_b32_e32 v156, v2
	v_mov_b32_e32 v157, v2
	v_mov_b32_e32 v158, v2
	v_mov_b32_e32 v159, v2
	v_mov_b32_e32 v160, v2
	v_mov_b32_e32 v161, v2

; #define PG8_BAR __builtin_amdgcn_s_barrier()
; template <class Epi, class Sched, bool ALIGN_EPI = false, bool SP2 = false>
; __device__ __forceinline__ void gemm_phase(PG8_LAS unsigned char* lds, const Gemm g, const Sched& S, const Epi& E) {
;     ...
;         if constexpr (!Epi::AFTER_DRAIN) { E(acc, cur, wr, wc, fr, fq); S.done(cur); }
;         if (!has_next) break;
; #pragma unroll
;         for (int a = 0; a < 2; ++a)
; #pragma unroll
;             for (int b = 0; b < 2; ++b)
; #pragma unroll
;                 for (int m = 0; m < 4; ++m)
; #pragma unroll
;                     for (int n = 0; n < 2; ++n) acc[a][b][m][n] = (f32x4){0.f, 0.f, 0.f, 0.f};
;         cur = nxt; cA = nA; cB = nB; ++ui;
;         if constexpr (ALIGN_EPI) { if (wr == 1) PG8_BAR; }
.LBB0_1152:
	s_or_b64 exec, exec, s[8:9]
	s_andn2_b64 vcc, exec, s[6:7]
	s_mov_b64 s[6:7], -1
	s_cbranch_vccnz .LBB0_1067
	s_mov_b32 s101, 0
	s_andn2_b64 vcc, exec, s[12:13]
	s_cbranch_vccnz .LBB0_1066
	s_mov_b32 s101, 1
	s_branch .LBB0_1066

; template <class Epi, class Sched, bool ALIGN_EPI = false, bool SP2 = false>
; __device__ __forceinline__ void gemm_phase(PG8_LAS unsigned char* lds, const Gemm g, const Sched& S, const Epi& E) {
;     ...
;         const bool has_next = S.next(ui + 1, nxt);
;         const char* nA = has_next ? (const char*)g.A + (size_t)nxt.pm * tstep : cA; const char* nB = has_next ? (const char*)g.Bt + (size_t)nxt.pn * tstep : cB;
;         for (int t = 0; t < nt; t += 2) {
;             const bool last = (t == nt - 2);
;             const char* a1 = cA + (size_t)(t + 1) * kstep;
;             const char* a2 = last ? nA : cA + (size_t)(t + 2) * kstep; const char* b2 = last ? nB : cB + (size_t)(t + 2) * kstep;
;             const char* a3 = a2 + kstep; const char* b3 = b2 + kstep;
;             if (last && has_next) S.a_ready(nxt);
.LBB0_1246:
	s_ashr_i32 s37, s36, 31
	s_lshl_b64 s[8:9], s[36:37], 19
	s_add_u32 s38, s2, s8
	s_addc_u32 s39, s49, s9
	s_and_b64 s[8:9], s[6:7], exec
	s_cselect_b32 s37, s39, s47
	s_cselect_b32 s43, s38, s46
	s_ashr_i32 s35, s34, 31
	s_lshl_b64 s[8:9], s[34:35], 19
	s_add_u32 s40, s50, s8
	s_addc_u32 s41, s51, s9
	s_and_b64 s[8:9], s[6:7], exec
	s_cselect_b32 s35, s41, s45
	s_cselect_b32 s65, s40, s44
	s_add_u32 s8, s46, 0x40080
	s_addc_u32 s9, s47, 0
	s_add_u32 s66, s44, 0x100
	s_addc_u32 s67, s45, 0
	s_mov_b32 s68, -2
	s_cmp_eq_u32 s101, 1
	s_cbranch_scc0 .Ldb2
	s_mov_b32 s101, 0
	s_barrier
.Ldb2:
.LBB0_1247:
	s_add_u32 s44, s8, 0xfffc0080
	s_addc_u32 s45, s9, -1
	s_add_i32 s69, 0, 0x10000
	s_cmp_eq_u32 s68, 12
	s_cselect_b32 s47, s37, s45
	s_cselect_b32 s46, s43, s44
	s_cselect_b32 s45, s35, s67
	s_cselect_b32 s44, s65, s66
	s_add_i32 s72, 0, 0x14000
	s_cmp_lg_u32 s68, 0
	s_cbranch_scc1 .Lffin_nopf
	s_cmp_lt_u32 s52, 0x1000
	s_cbranch_scc0 .Lffin_pf_w
	s_lshl_b32 s98, s42, 12
	s_add_u32 s98, s12, s98
	s_addc_u32 s99, s13, 0
	v_lshlrev_b32_e32 v232, 4, v174
	s_add_i32 m0, s52, 0x21000
	s_nop 0
	global_load_lds_dwordx4 v232, s[98:99]
	s_branch .Lffin_nopf

;     __device__ __forceinline__ void operator()(const f32x4 (&acc)[2][2][4][2], const Unit& u, int wr, int wc, int fr, int fq) const {
;     ...
;             for (int m = 0; m < 4; ++m) {
;                 const int row = row0 + ai * HALF + m * 16; const float rs = rsv[m];
;                 const f32x4 ca = acc[ai][0][m][0] * rs, cb_ = acc[ai][0][m][1] * rs;
;                 f32x4 aa = w2a * ca + ba, ab = w2b * cb_ + bb;
; #pragma unroll
;                 for (int c = 0; c < 4; ++c) { aa[c] = __builtin_fmaf(w1a[c], dpp_shr1(ca[c]), aa[c]); ab[c] = __builtin_fmaf(w1b[c], dpp_shr1(cb_[c]), ab[c]);
;                     aa[c] = __builtin_fmaf(w0a[c], dpp_shr2(ca[c]), aa[c]); ab[c] = __builtin_fmaf(w0b[c], dpp_shr2(cb_[c]), ab[c]); }
;                 if (m == 0) {
;                     if (ai == 1 || wr == 1) { const int sw = ((ai == 1 && wr == 0) ? 4 : 0) + wc, sai = (ai == 1 && wr == 1) ? 1 : 0;
;                         const PG8_LAS f32x4* xp = (const PG8_LAS f32x4*)(X + ((sw * 2 + sai) * 2) * 32 + fq * 8); const f32x4 h0a = xp[0], h0b = xp[1], h1a = xp[8], h1b = xp[9];
;                         aa += w1a * (h1a * m0) + w0a * (h0a * m0 + h1a * m1); ab += w1b * (h1b * m0) + w0b * (h0b * m0 + h1b * m1); }
;                 } else {
; #pragma unroll
;                     for (int c = 0; c < 4; ++c) { aa[c] = __builtin_fmaf(w1a[c], dpp_shl15(pa[c]), aa[c]); ab[c] = __builtin_fmaf(w1b[c], dpp_shl15(pb[c]), ab[c]);
;                         aa[c] = __builtin_fmaf(w0a[c], dpp_shl14(pa[c]), aa[c]); ab[c] = __builtin_fmaf(w0b[c], dpp_shl14(pb[c]), ab[c]); }
;                 }
;                 const f32x4 ga = acc[ai][1][m][0] * rs, gb = acc[ai][1][m][1] * rs;
;                 f32x4 ea = aa * -1.4426950408889634f, eb = ab * -1.4426950408889634f;
; #pragma unroll
;                 for (int c = 0; c < 4; ++c) { ea[c] = __builtin_amdgcn_exp2f(ea[c]); eb[c] = __builtin_amdgcn_exp2f(eb[c]); }
;                 ea = ea + 1.0f; eb = eb + 1.0f;
; #pragma unroll
;                 for (int c = 0; c < 4; ++c) { ea[c] = __builtin_amdgcn_rcpf(ea[c]); eb[c] = __builtin_amdgcn_rcpf(eb[c]); }
;                 const f32x4 oa = (aa * ga) * ea, ob = (ab * gb) * eb;
;                 u32x4 w; w.x = cvt_pk_bf16(oa[0], oa[1]); w.y = cvt_pk_bf16(oa[2], oa[3]); w.z = cvt_pk_bf16(ob[0], ob[1]); w.w = cvt_pk_bf16(ob[2], ob[3]);
;                 *(u32x4*)(act + (size_t)row * FF + col) = w;
.Lffin_nopark:
	s_or_b64 exec, exec, s[46:47]
	v_pk_mul_f32 v[244:245], v[236:237], s[92:93] op_sel_hi:[1,0]
	v_pk_mul_f32 v[246:247], v[238:239], s[92:93] op_sel_hi:[1,0]
	v_pk_mul_f32 v[248:249], v[240:241], s[92:93] op_sel_hi:[1,0]
	v_pk_mul_f32 v[250:251], v[242:243], s[92:93] op_sel_hi:[1,0]
	v_exp_f32_e32 v244, v244
	v_exp_f32_e32 v245, v245
	v_exp_f32_e32 v246, v246
	v_exp_f32_e32 v247, v247
	v_exp_f32_e32 v248, v248
	v_exp_f32_e32 v249, v249
	v_exp_f32_e32 v250, v250
	v_exp_f32_e32 v251, v251
	v_pk_mul_f32 v[236:237], v[236:237], v[150:151]
	v_pk_mul_f32 v[238:239], v[238:239], v[152:153]
	v_pk_mul_f32 v[240:241], v[240:241], v[146:147]
	v_pk_mul_f32 v[242:243], v[242:243], v[148:149]
	v_pk_add_f32 v[244:245], v[244:245], 1.0 op_sel_hi:[1,0]
	v_pk_add_f32 v[246:247], v[246:247], 1.0 op_sel_hi:[1,0]
	v_pk_add_f32 v[248:249], v[248:249], 1.0 op_sel_hi:[1,0]
	v_pk_add_f32 v[250:251], v[250:251], 1.0 op_sel_hi:[1,0]
	v_rcp_f32_e32 v244, v244
	v_rcp_f32_e32 v245, v245
	v_rcp_f32_e32 v246, v246
	v_rcp_f32_e32 v247, v247
	v_rcp_f32_e32 v248, v248
	v_rcp_f32_e32 v249, v249
	v_rcp_f32_e32 v250, v250
	v_rcp_f32_e32 v251, v251
	s_nop 0
	v_pk_mul_f32 v[236:237], v[236:237], v[244:245]
	v_pk_mul_f32 v[238:239], v[238:239], v[246:247]
	v_pk_mul_f32 v[240:241], v[240:241], v[248:249]
	v_pk_mul_f32 v[242:243], v[242:243], v[250:251]
	v_cvt_pk_bf16_f32 v216, v236, v237
	v_cvt_pk_bf16_f32 v217, v238, v239
	v_cvt_pk_bf16_f32 v218, v240, v241
	v_cvt_pk_bf16_f32 v219, v242, v243
	global_store_dwordx4 v[220:221], v[216:219], off sc1
	v_lshl_add_u64 v[220:221], v[220:221], 0, s[100:101]
	v_pk_mul_f32 v[142:143], v[142:143], v[164:165] op_sel_hi:[1,0]
	v_pk_mul_f32 v[144:145], v[144:145], v[164:165] op_sel_hi:[1,0]
	v_pk_mul_f32 v[138:139], v[138:139], v[164:165] op_sel_hi:[1,0]
	v_pk_mul_f32 v[140:141], v[140:141], v[164:165] op_sel_hi:[1,0]
	v_pk_fma_f32 v[236:237], v[122:123], v[142:143], v[130:131]
	v_pk_fma_f32 v[238:239], v[124:125], v[144:145], v[132:133]
	v_pk_fma_f32 v[240:241], v[126:127], v[138:139], v[134:135]
	v_pk_fma_f32 v[242:243], v[128:129], v[140:141], v[136:137]
	v_pk_mul_f32 v[102:103], v[102:103], v[164:165] op_sel_hi:[1,0]
	v_pk_mul_f32 v[104:105], v[104:105], v[164:165] op_sel_hi:[1,0]
	v_pk_mul_f32 v[98:99], v[98:99], v[164:165] op_sel_hi:[1,0]
	v_pk_mul_f32 v[100:101], v[100:101], v[164:165] op_sel_hi:[1,0]
	v_fmac_f32_dpp v236, v142, v114 row_shr:1 row_mask:0xf bank_mask:0xf bound_ctrl:1
	v_fmac_f32_dpp v237, v143, v115 row_shr:1 row_mask:0xf bank_mask:0xf bound_ctrl:1
	v_fmac_f32_dpp v238, v144, v116 row_shr:1 row_mask:0xf bank_mask:0xf bound_ctrl:1
	v_fmac_f32_dpp v239, v145, v117 row_shr:1 row_mask:0xf bank_mask:0xf bound_ctrl:1
	v_fmac_f32_dpp v240, v138, v118 row_shr:1 row_mask:0xf bank_mask:0xf bound_ctrl:1
	v_fmac_f32_dpp v241, v139, v119 row_shr:1 row_mask:0xf bank_mask:0xf bound_ctrl:1
	v_fmac_f32_dpp v242, v140, v120 row_shr:1 row_mask:0xf bank_mask:0xf bound_ctrl:1
	v_fmac_f32_dpp v243, v141, v121 row_shr:1 row_mask:0xf bank_mask:0xf bound_ctrl:1
	v_fmac_f32_dpp v236, v142, v106 row_shr:2 row_mask:0xf bank_mask:0xf bound_ctrl:1
	v_fmac_f32_dpp v237, v143, v107 row_shr:2 row_mask:0xf bank_mask:0xf bound_ctrl:1
	v_fmac_f32_dpp v238, v144, v108 row_shr:2 row_mask:0xf bank_mask:0xf bound_ctrl:1
	v_fmac_f32_dpp v239, v145, v109 row_shr:2 row_mask:0xf bank_mask:0xf bound_ctrl:1
	v_fmac_f32_dpp v240, v138, v110 row_shr:2 row_mask:0xf bank_mask:0xf bound_ctrl:1
	v_fmac_f32_dpp v241, v139, v111 row_shr:2 row_mask:0xf bank_mask:0xf bound_ctrl:1
	v_fmac_f32_dpp v242, v140, v112 row_shr:2 row_mask:0xf bank_mask:0xf bound_ctrl:1
	v_fmac_f32_dpp v243, v141, v113 row_shr:2 row_mask:0xf bank_mask:0xf bound_ctrl:1
	v_fmac_f32_dpp v236, v158, v114 row_shl:15 row_mask:0xf bank_mask:0xf bound_ctrl:1
	v_fmac_f32_dpp v237, v159, v115 row_shl:15 row_mask:0xf bank_mask:0xf bound_ctrl:1
	v_fmac_f32_dpp v238, v160, v116 row_shl:15 row_mask:0xf bank_mask:0xf bound_ctrl:1
	v_fmac_f32_dpp v239, v161, v117 row_shl:15 row_mask:0xf bank_mask:0xf bound_ctrl:1
	v_fmac_f32_dpp v240, v154, v118 row_shl:15 row_mask:0xf bank_mask:0xf bound_ctrl:1
	v_fmac_f32_dpp v241, v155, v119 row_shl:15 row_mask:0xf bank_mask:0xf bound_ctrl:1
	v_fmac_f32_dpp v242, v156, v120 row_shl:15 row_mask:0xf bank_mask:0xf bound_ctrl:1
	v_fmac_f32_dpp v243, v157, v121 row_shl:15 row_mask:0xf bank_mask:0xf bound_ctrl:1
	v_fmac_f32_dpp v236, v158, v106 row_shl:14 row_mask:0xf bank_mask:0xf bound_ctrl:1
	v_fmac_f32_dpp v237, v159, v107 row_shl:14 row_mask:0xf bank_mask:0xf bound_ctrl:1
	v_fmac_f32_dpp v238, v160, v108 row_shl:14 row_mask:0xf bank_mask:0xf bound_ctrl:1
	v_fmac_f32_dpp v239, v161, v109 row_shl:14 row_mask:0xf bank_mask:0xf bound_ctrl:1
	v_fmac_f32_dpp v240, v154, v110 row_shl:14 row_mask:0xf bank_mask:0xf bound_ctrl:1
	v_fmac_f32_dpp v241, v155, v111 row_shl:14 row_mask:0xf bank_mask:0xf bound_ctrl:1
	v_fmac_f32_dpp v242, v156, v112 row_shl:14 row_mask:0xf bank_mask:0xf bound_ctrl:1
	v_fmac_f32_dpp v243, v157, v113 row_shl:14 row_mask:0xf bank_mask:0xf bound_ctrl:1
	v_pk_mul_f32 v[244:245], v[236:237], s[92:93] op_sel_hi:[1,0]
	v_pk_mul_f32 v[246:247], v[238:239], s[92:93] op_sel_hi:[1,0]
	v_pk_mul_f32 v[248:249], v[240:241], s[92:93] op_sel_hi:[1,0]
	v_pk_mul_f32 v[250:251], v[242:243], s[92:93] op_sel_hi:[1,0]
	v_exp_f32_e32 v244, v244
	v_exp_f32_e32 v245, v245
	v_exp_f32_e32 v246, v246
	v_exp_f32_e32 v247, v247
	v_exp_f32_e32 v248, v248
	v_exp_f32_e32 v249, v249
	v_exp_f32_e32 v250, v250
	v_exp_f32_e32 v251, v251
	v_pk_mul_f32 v[236:237], v[236:237], v[102:103]
	v_pk_mul_f32 v[238:239], v[238:239], v[104:105]
	v_pk_mul_f32 v[240:241], v[240:241], v[98:99]
;     __device__ __forceinline__ void operator()(const f32x4 (&acc)[2][2][4][2], const Unit& u, int wr, int wc, int fr, int fq) const {
;     ...
;             for (int m = 0; m < 4; ++m) {
;                 const int row = row0 + ai * HALF + m * 16; const float rs = rsv[m];
;                 const f32x4 ca = acc[ai][0][m][0] * rs, cb_ = acc[ai][0][m][1] * rs;
;                 f32x4 aa = w2a * ca + ba, ab = w2b * cb_ + bb;
; #pragma unroll
;                 for (int c = 0; c < 4; ++c) { aa[c] = __builtin_fmaf(w1a[c], dpp_shr1(ca[c]), aa[c]); ab[c] = __builtin_fmaf(w1b[c], dpp_shr1(cb_[c]), ab[c]);
;                     aa[c] = __builtin_fmaf(w0a[c], dpp_shr2(ca[c]), aa[c]); ab[c] = __builtin_fmaf(w0b[c], dpp_shr2(cb_[c]), ab[c]); }
;                 if (m == 0) {
;                     if (ai == 1 || wr == 1) { const int sw = ((ai == 1 && wr == 0) ? 4 : 0) + wc, sai = (ai == 1 && wr == 1) ? 1 : 0;
;                         const PG8_LAS f32x4* xp = (const PG8_LAS f32x4*)(X + ((sw * 2 + sai) * 2) * 32 + fq * 8); const f32x4 h0a = xp[0], h0b = xp[1], h1a = xp[8], h1b = xp[9];
;                         aa += w1a * (h1a * m0) + w0a * (h0a * m0 + h1a * m1); ab += w1b * (h1b * m0) + w0b * (h0b * m0 + h1b * m1); }
;                 } else {
; #pragma unroll
;                     for (int c = 0; c < 4; ++c) { aa[c] = __builtin_fmaf(w1a[c], dpp_shl15(pa[c]), aa[c]); ab[c] = __builtin_fmaf(w1b[c], dpp_shl15(pb[c]), ab[c]);
;                         aa[c] = __builtin_fmaf(w0a[c], dpp_shl14(pa[c]), aa[c]); ab[c] = __builtin_fmaf(w0b[c], dpp_shl14(pb[c]), ab[c]); }
;                 }
;                 const f32x4 ga = acc[ai][1][m][0] * rs, gb = acc[ai][1][m][1] * rs;
;                 f32x4 ea = aa * -1.4426950408889634f, eb = ab * -1.4426950408889634f;
; #pragma unroll
;                 for (int c = 0; c < 4; ++c) { ea[c] = __builtin_amdgcn_exp2f(ea[c]); eb[c] = __builtin_amdgcn_exp2f(eb[c]); }
;                 ea = ea + 1.0f; eb = eb + 1.0f;
; #pragma unroll
;                 for (int c = 0; c < 4; ++c) { ea[c] = __builtin_amdgcn_rcpf(ea[c]); eb[c] = __builtin_amdgcn_rcpf(eb[c]); }
;                 const f32x4 oa = (aa * ga) * ea, ob = (ab * gb) * eb;
;                 u32x4 w; w.x = cvt_pk_bf16(oa[0], oa[1]); w.y = cvt_pk_bf16(oa[2], oa[3]); w.z = cvt_pk_bf16(ob[0], ob[1]); w.w = cvt_pk_bf16(ob[2], ob[3]);
;                 *(u32x4*)(act + (size_t)row * FF + col) = w;
	v_pk_mul_f32 v[242:243], v[242:243], v[100:101]
	v_pk_add_f32 v[244:245], v[244:245], 1.0 op_sel_hi:[1,0]
	v_pk_add_f32 v[246:247], v[246:247], 1.0 op_sel_hi:[1,0]
	v_pk_add_f32 v[248:249], v[248:249], 1.0 op_sel_hi:[1,0]
	v_pk_add_f32 v[250:251], v[250:251], 1.0 op_sel_hi:[1,0]
	v_rcp_f32_e32 v244, v244
	v_rcp_f32_e32 v245, v245
	v_rcp_f32_e32 v246, v246
	v_rcp_f32_e32 v247, v247
	v_rcp_f32_e32 v248, v248
	v_rcp_f32_e32 v249, v249
	v_rcp_f32_e32 v250, v250
	v_rcp_f32_e32 v251, v251
	s_nop 0
	v_pk_mul_f32 v[236:237], v[236:237], v[244:245]
	v_pk_mul_f32 v[238:239], v[238:239], v[246:247]
	v_pk_mul_f32 v[240:241], v[240:241], v[248:249]
	v_pk_mul_f32 v[242:243], v[242:243], v[250:251]
	v_cvt_pk_bf16_f32 v216, v236, v237
	v_cvt_pk_bf16_f32 v217, v238, v239
	v_cvt_pk_bf16_f32 v218, v240, v241
	v_cvt_pk_bf16_f32 v219, v242, v243
	global_store_dwordx4 v[220:221], v[216:219], off sc1
	v_lshl_add_u64 v[220:221], v[220:221], 0, s[100:101]
	v_pk_mul_f32 v[94:95], v[94:95], v[166:167] op_sel_hi:[1,0]
	v_pk_mul_f32 v[96:97], v[96:97], v[166:167] op_sel_hi:[1,0]
	v_pk_mul_f32 v[90:91], v[90:91], v[166:167] op_sel_hi:[1,0]
	v_pk_mul_f32 v[92:93], v[92:93], v[166:167] op_sel_hi:[1,0]
	v_pk_fma_f32 v[236:237], v[122:123], v[94:95], v[130:131]
	v_pk_fma_f32 v[238:239], v[124:125], v[96:97], v[132:133]
	v_pk_fma_f32 v[240:241], v[126:127], v[90:91], v[134:135]
	v_pk_fma_f32 v[242:243], v[128:129], v[92:93], v[136:137]
	v_pk_mul_f32 v[86:87], v[86:87], v[166:167] op_sel_hi:[1,0]
	v_pk_mul_f32 v[88:89], v[88:89], v[166:167] op_sel_hi:[1,0]
	v_pk_mul_f32 v[82:83], v[82:83], v[166:167] op_sel_hi:[1,0]
	v_pk_mul_f32 v[84:85], v[84:85], v[166:167] op_sel_hi:[1,0]
	v_fmac_f32_dpp v236, v94, v114 row_shr:1 row_mask:0xf bank_mask:0xf bound_ctrl:1
	v_fmac_f32_dpp v237, v95, v115 row_shr:1 row_mask:0xf bank_mask:0xf bound_ctrl:1
	v_fmac_f32_dpp v238, v96, v116 row_shr:1 row_mask:0xf bank_mask:0xf bound_ctrl:1
	v_fmac_f32_dpp v239, v97, v117 row_shr:1 row_mask:0xf bank_mask:0xf bound_ctrl:1
	v_fmac_f32_dpp v240, v90, v118 row_shr:1 row_mask:0xf bank_mask:0xf bound_ctrl:1
	v_fmac_f32_dpp v241, v91, v119 row_shr:1 row_mask:0xf bank_mask:0xf bound_ctrl:1
	v_fmac_f32_dpp v242, v92, v120 row_shr:1 row_mask:0xf bank_mask:0xf bound_ctrl:1
	v_fmac_f32_dpp v243, v93, v121 row_shr:1 row_mask:0xf bank_mask:0xf bound_ctrl:1
	v_fmac_f32_dpp v236, v94, v106 row_shr:2 row_mask:0xf bank_mask:0xf bound_ctrl:1
	v_fmac_f32_dpp v237, v95, v107 row_shr:2 row_mask:0xf bank_mask:0xf bound_ctrl:1
	v_fmac_f32_dpp v238, v96, v108 row_shr:2 row_mask:0xf bank_mask:0xf bound_ctrl:1
	v_fmac_f32_dpp v239, v97, v109 row_shr:2 row_mask:0xf bank_mask:0xf bound_ctrl:1
	v_fmac_f32_dpp v240, v90, v110 row_shr:2 row_mask:0xf bank_mask:0xf bound_ctrl:1
	v_fmac_f32_dpp v241, v91, v111 row_shr:2 row_mask:0xf bank_mask:0xf bound_ctrl:1
	v_fmac_f32_dpp v242, v92, v112 row_shr:2 row_mask:0xf bank_mask:0xf bound_ctrl:1
	v_fmac_f32_dpp v243, v93, v113 row_shr:2 row_mask:0xf bank_mask:0xf bound_ctrl:1
	v_fmac_f32_dpp v236, v142, v114 row_shl:15 row_mask:0xf bank_mask:0xf bound_ctrl:1
	v_fmac_f32_dpp v237, v143, v115 row_shl:15 row_mask:0xf bank_mask:0xf bound_ctrl:1
	v_fmac_f32_dpp v238, v144, v116 row_shl:15 row_mask:0xf bank_mask:0xf bound_ctrl:1
	v_fmac_f32_dpp v239, v145, v117 row_shl:15 row_mask:0xf bank_mask:0xf bound_ctrl:1
	v_fmac_f32_dpp v240, v138, v118 row_shl:15 row_mask:0xf bank_mask:0xf bound_ctrl:1
	v_fmac_f32_dpp v241, v139, v119 row_shl:15 row_mask:0xf bank_mask:0xf bound_ctrl:1
	v_fmac_f32_dpp v242, v140, v120 row_shl:15 row_mask:0xf bank_mask:0xf bound_ctrl:1
	v_fmac_f32_dpp v243, v141, v121 row_shl:15 row_mask:0xf bank_mask:0xf bound_ctrl:1
	v_fmac_f32_dpp v236, v142, v106 row_shl:14 row_mask:0xf bank_mask:0xf bound_ctrl:1
	v_fmac_f32_dpp v237, v143, v107 row_shl:14 row_mask:0xf bank_mask:0xf bound_ctrl:1
	v_fmac_f32_dpp v238, v144, v108 row_shl:14 row_mask:0xf bank_mask:0xf bound_ctrl:1
	v_fmac_f32_dpp v239, v145, v109 row_shl:14 row_mask:0xf bank_mask:0xf bound_ctrl:1
	v_fmac_f32_dpp v240, v138, v110 row_shl:14 row_mask:0xf bank_mask:0xf bound_ctrl:1
	v_fmac_f32_dpp v241, v139, v111 row_shl:14 row_mask:0xf bank_mask:0xf bound_ctrl:1
	v_fmac_f32_dpp v242, v140, v112 row_shl:14 row_mask:0xf bank_mask:0xf bound_ctrl:1
	v_fmac_f32_dpp v243, v141, v113 row_shl:14 row_mask:0xf bank_mask:0xf bound_ctrl:1
	v_pk_mul_f32 v[244:245], v[236:237], s[92:93] op_sel_hi:[1,0]
	v_pk_mul_f32 v[246:247], v[238:239], s[92:93] op_sel_hi:[1,0]
	v_pk_mul_f32 v[248:249], v[240:241], s[92:93] op_sel_hi:[1,0]
	v_pk_mul_f32 v[250:251], v[242:243], s[92:93] op_sel_hi:[1,0]
	v_exp_f32_e32 v244, v244
	v_exp_f32_e32 v245, v245
	v_exp_f32_e32 v246, v246
	v_exp_f32_e32 v247, v247
	v_exp_f32_e32 v248, v248
	v_exp_f32_e32 v249, v249
	v_exp_f32_e32 v250, v250
	v_exp_f32_e32 v251, v251
	v_pk_mul_f32 v[236:237], v[236:237], v[86:87]
	v_pk_mul_f32 v[238:239], v[238:239], v[88:89]
	v_pk_mul_f32 v[240:241], v[240:241], v[82:83]
	v_pk_mul_f32 v[242:243], v[242:243], v[84:85]
	v_pk_add_f32 v[244:245], v[244:245], 1.0 op_sel_hi:[1,0]
	v_pk_add_f32 v[246:247], v[246:247], 1.0 op_sel_hi:[1,0]
	v_pk_add_f32 v[248:249], v[248:249], 1.0 op_sel_hi:[1,0]
	v_pk_add_f32 v[250:251], v[250:251], 1.0 op_sel_hi:[1,0]
	v_rcp_f32_e32 v244, v244
	v_rcp_f32_e32 v245, v245
	v_rcp_f32_e32 v246, v246
	v_rcp_f32_e32 v247, v247
	v_rcp_f32_e32 v248, v248
	v_rcp_f32_e32 v249, v249
	v_rcp_f32_e32 v250, v250
	v_rcp_f32_e32 v251, v251
	s_nop 0
	v_pk_mul_f32 v[236:237], v[236:237], v[244:245]
	v_pk_mul_f32 v[238:239], v[238:239], v[246:247]
	v_pk_mul_f32 v[240:241], v[240:241], v[248:249]
	v_pk_mul_f32 v[242:243], v[242:243], v[250:251]
	v_cvt_pk_bf16_f32 v216, v236, v237
;     __device__ __forceinline__ void operator()(const f32x4 (&acc)[2][2][4][2], const Unit& u, int wr, int wc, int fr, int fq) const {
;     ...
;         for (int ai = 0; ai < 2; ++ai) {
;             f32x4 pa = {0.f, 0.f, 0.f, 0.f}, pb = {0.f, 0.f, 0.f, 0.f};
;             float rsv[4];
; #pragma unroll
;             for (int m = 0; m < 4; ++m) rsv[m] = row_rstd(ssq, row0 + ai * HALF + m * 16);
; #pragma unroll
;             for (int m = 0; m < 4; ++m) {
;                 const int row = row0 + ai * HALF + m * 16; const float rs = rsv[m];
;                 const f32x4 ca = acc[ai][0][m][0] * rs, cb_ = acc[ai][0][m][1] * rs;
;                 f32x4 aa = w2a * ca + ba, ab = w2b * cb_ + bb;
; #pragma unroll
;                 for (int c = 0; c < 4; ++c) { aa[c] = __builtin_fmaf(w1a[c], dpp_shr1(ca[c]), aa[c]); ab[c] = __builtin_fmaf(w1b[c], dpp_shr1(cb_[c]), ab[c]);
;                     aa[c] = __builtin_fmaf(w0a[c], dpp_shr2(ca[c]), aa[c]); ab[c] = __builtin_fmaf(w0b[c], dpp_shr2(cb_[c]), ab[c]); }
;                 if (m == 0) {
;                     if (ai == 1 || wr == 1) { const int sw = ((ai == 1 && wr == 0) ? 4 : 0) + wc, sai = (ai == 1 && wr == 1) ? 1 : 0;
;                         const PG8_LAS f32x4* xp = (const PG8_LAS f32x4*)(X + ((sw * 2 + sai) * 2) * 32 + fq * 8); const f32x4 h0a = xp[0], h0b = xp[1], h1a = xp[8], h1b = xp[9];
;                         aa += w1a * (h1a * m0) + w0a * (h0a * m0 + h1a * m1); ab += w1b * (h1b * m0) + w0b * (h0b * m0 + h1b * m1); }
;                 } else {
; #pragma unroll
;                     for (int c = 0; c < 4; ++c) { aa[c] = __builtin_fmaf(w1a[c], dpp_shl15(pa[c]), aa[c]); ab[c] = __builtin_fmaf(w1b[c], dpp_shl15(pb[c]), ab[c]);
;                         aa[c] = __builtin_fmaf(w0a[c], dpp_shl14(pa[c]), aa[c]); ab[c] = __builtin_fmaf(w0b[c], dpp_shl14(pb[c]), ab[c]); }
;                 }
;                 const f32x4 ga = acc[ai][1][m][0] * rs, gb = acc[ai][1][m][1] * rs;
;                 f32x4 ea = aa * -1.4426950408889634f, eb = ab * -1.4426950408889634f;
; #pragma unroll
;                 for (int c = 0; c < 4; ++c) { ea[c] = __builtin_amdgcn_exp2f(ea[c]); eb[c] = __builtin_amdgcn_exp2f(eb[c]); }
;                 ea = ea + 1.0f; eb = eb + 1.0f;
; #pragma unroll
;                 for (int c = 0; c < 4; ++c) { ea[c] = __builtin_amdgcn_rcpf(ea[c]); eb[c] = __builtin_amdgcn_rcpf(eb[c]); }
	v_cvt_pk_bf16_f32 v217, v238, v239
	v_cvt_pk_bf16_f32 v218, v240, v241
	v_cvt_pk_bf16_f32 v219, v242, v243
	global_store_dwordx4 v[220:221], v[216:219], off sc1
	v_lshl_add_u64 v[220:221], v[220:221], 0, s[100:101]
	v_pk_fma_f32 v[236:237], v[122:123], v[78:79], v[130:131]
	v_pk_fma_f32 v[238:239], v[124:125], v[80:81], v[132:133]
	v_pk_fma_f32 v[240:241], v[126:127], v[74:75], v[134:135]
	v_pk_fma_f32 v[242:243], v[128:129], v[76:77], v[136:137]
	v_pk_mul_f32 v[70:71], v[70:71], v[168:169] op_sel_hi:[1,0]
	v_pk_mul_f32 v[72:73], v[72:73], v[168:169] op_sel_hi:[1,0]
	v_pk_mul_f32 v[66:67], v[66:67], v[168:169] op_sel_hi:[1,0]
	v_pk_mul_f32 v[68:69], v[68:69], v[168:169] op_sel_hi:[1,0]
	v_fmac_f32_dpp v236, v78, v114 row_shr:1 row_mask:0xf bank_mask:0xf bound_ctrl:1
	v_fmac_f32_dpp v237, v79, v115 row_shr:1 row_mask:0xf bank_mask:0xf bound_ctrl:1
	v_fmac_f32_dpp v238, v80, v116 row_shr:1 row_mask:0xf bank_mask:0xf bound_ctrl:1
	v_fmac_f32_dpp v239, v81, v117 row_shr:1 row_mask:0xf bank_mask:0xf bound_ctrl:1
	v_fmac_f32_dpp v240, v74, v118 row_shr:1 row_mask:0xf bank_mask:0xf bound_ctrl:1
	v_fmac_f32_dpp v241, v75, v119 row_shr:1 row_mask:0xf bank_mask:0xf bound_ctrl:1
	v_fmac_f32_dpp v242, v76, v120 row_shr:1 row_mask:0xf bank_mask:0xf bound_ctrl:1
	v_fmac_f32_dpp v243, v77, v121 row_shr:1 row_mask:0xf bank_mask:0xf bound_ctrl:1
	v_fmac_f32_dpp v236, v78, v106 row_shr:2 row_mask:0xf bank_mask:0xf bound_ctrl:1
	v_fmac_f32_dpp v237, v79, v107 row_shr:2 row_mask:0xf bank_mask:0xf bound_ctrl:1
	v_fmac_f32_dpp v238, v80, v108 row_shr:2 row_mask:0xf bank_mask:0xf bound_ctrl:1
	v_fmac_f32_dpp v239, v81, v109 row_shr:2 row_mask:0xf bank_mask:0xf bound_ctrl:1
	v_fmac_f32_dpp v240, v74, v110 row_shr:2 row_mask:0xf bank_mask:0xf bound_ctrl:1
	v_fmac_f32_dpp v241, v75, v111 row_shr:2 row_mask:0xf bank_mask:0xf bound_ctrl:1
	v_fmac_f32_dpp v242, v76, v112 row_shr:2 row_mask:0xf bank_mask:0xf bound_ctrl:1
	v_fmac_f32_dpp v243, v77, v113 row_shr:2 row_mask:0xf bank_mask:0xf bound_ctrl:1
	v_fmac_f32_dpp v236, v94, v114 row_shl:15 row_mask:0xf bank_mask:0xf bound_ctrl:1
	v_fmac_f32_dpp v237, v95, v115 row_shl:15 row_mask:0xf bank_mask:0xf bound_ctrl:1
	v_fmac_f32_dpp v238, v96, v116 row_shl:15 row_mask:0xf bank_mask:0xf bound_ctrl:1
	v_fmac_f32_dpp v239, v97, v117 row_shl:15 row_mask:0xf bank_mask:0xf bound_ctrl:1
	v_fmac_f32_dpp v240, v90, v118 row_shl:15 row_mask:0xf bank_mask:0xf bound_ctrl:1
	v_fmac_f32_dpp v241, v91, v119 row_shl:15 row_mask:0xf bank_mask:0xf bound_ctrl:1
	v_fmac_f32_dpp v242, v92, v120 row_shl:15 row_mask:0xf bank_mask:0xf bound_ctrl:1
	v_fmac_f32_dpp v243, v93, v121 row_shl:15 row_mask:0xf bank_mask:0xf bound_ctrl:1
	v_fmac_f32_dpp v236, v94, v106 row_shl:14 row_mask:0xf bank_mask:0xf bound_ctrl:1
	v_fmac_f32_dpp v237, v95, v107 row_shl:14 row_mask:0xf bank_mask:0xf bound_ctrl:1
	v_fmac_f32_dpp v238, v96, v108 row_shl:14 row_mask:0xf bank_mask:0xf bound_ctrl:1
	v_fmac_f32_dpp v239, v97, v109 row_shl:14 row_mask:0xf bank_mask:0xf bound_ctrl:1
	v_fmac_f32_dpp v240, v90, v110 row_shl:14 row_mask:0xf bank_mask:0xf bound_ctrl:1
	v_fmac_f32_dpp v241, v91, v111 row_shl:14 row_mask:0xf bank_mask:0xf bound_ctrl:1
	v_fmac_f32_dpp v242, v92, v112 row_shl:14 row_mask:0xf bank_mask:0xf bound_ctrl:1
	v_fmac_f32_dpp v243, v93, v113 row_shl:14 row_mask:0xf bank_mask:0xf bound_ctrl:1
	v_pk_mul_f32 v[244:245], v[236:237], s[92:93] op_sel_hi:[1,0]
	v_pk_mul_f32 v[246:247], v[238:239], s[92:93] op_sel_hi:[1,0]
	v_pk_mul_f32 v[248:249], v[240:241], s[92:93] op_sel_hi:[1,0]
	v_pk_mul_f32 v[250:251], v[242:243], s[92:93] op_sel_hi:[1,0]
	v_exp_f32_e32 v244, v244
	v_exp_f32_e32 v245, v245
	v_exp_f32_e32 v246, v246
	v_exp_f32_e32 v247, v247
	v_exp_f32_e32 v248, v248
	v_exp_f32_e32 v249, v249
	v_exp_f32_e32 v250, v250
	v_exp_f32_e32 v251, v251
	v_pk_mul_f32 v[236:237], v[236:237], v[70:71]
	v_pk_mul_f32 v[238:239], v[238:239], v[72:73]
	v_pk_mul_f32 v[240:241], v[240:241], v[66:67]
	v_pk_mul_f32 v[242:243], v[242:243], v[68:69]
	v_pk_add_f32 v[244:245], v[244:245], 1.0 op_sel_hi:[1,0]
	v_pk_add_f32 v[246:247], v[246:247], 1.0 op_sel_hi:[1,0]
	v_pk_add_f32 v[248:249], v[248:249], 1.0 op_sel_hi:[1,0]
	v_pk_add_f32 v[250:251], v[250:251], 1.0 op_sel_hi:[1,0]
	v_rcp_f32_e32 v244, v244
	v_rcp_f32_e32 v245, v245
	v_rcp_f32_e32 v246, v246
	v_rcp_f32_e32 v247, v247
	v_rcp_f32_e32 v248, v248
	v_rcp_f32_e32 v249, v249
	v_rcp_f32_e32 v250, v250
	v_rcp_f32_e32 v251, v251
	s_nop 0
	v_pk_mul_f32 v[236:237], v[236:237], v[244:245]
	v_pk_mul_f32 v[238:239], v[238:239], v[246:247]
	v_pk_mul_f32 v[240:241], v[240:241], v[248:249]
	v_pk_mul_f32 v[242:243], v[242:243], v[250:251]
	v_cvt_pk_bf16_f32 v216, v236, v237
	v_cvt_pk_bf16_f32 v217, v238, v239
	v_cvt_pk_bf16_f32 v218, v240, v241
	v_cvt_pk_bf16_f32 v219, v242, v243
	global_store_dwordx4 v[220:221], v[216:219], off sc1
	v_lshl_add_u64 v[220:221], v[220:221], 0, s[98:99]
	v_pk_mul_f32 v[62:63], v[62:63], v[170:171] op_sel_hi:[1,0]
	v_pk_mul_f32 v[64:65], v[64:65], v[170:171] op_sel_hi:[1,0]
	v_pk_mul_f32 v[58:59], v[58:59], v[170:171] op_sel_hi:[1,0]
	v_pk_mul_f32 v[60:61], v[60:61], v[170:171] op_sel_hi:[1,0]
	v_lshl_add_u32 v167, v163, 2, s64
	ds_read_b128 v[192:195], v167
	ds_read_b128 v[196:199], v167 offset:16
	ds_read_b128 v[200:203], v167 offset:128
	ds_read_b128 v[204:207], v167 offset:144
	v_pk_fma_f32 v[236:237], v[122:123], v[62:63], v[130:131]
	v_pk_fma_f32 v[238:239], v[124:125], v[64:65], v[132:133]
	v_pk_fma_f32 v[240:241], v[126:127], v[58:59], v[134:135]
	v_pk_fma_f32 v[242:243], v[128:129], v[60:61], v[136:137]
	v_pk_mul_f32 v[54:55], v[54:55], v[170:171] op_sel_hi:[1,0]
;     __device__ __forceinline__ void operator()(const f32x4 (&acc)[2][2][4][2], const Unit& u, int wr, int wc, int fr, int fq) const {
;     ...
;             for (int m = 0; m < 4; ++m) {
;                 const int row = row0 + ai * HALF + m * 16; const float rs = rsv[m];
;                 const f32x4 ca = acc[ai][0][m][0] * rs, cb_ = acc[ai][0][m][1] * rs;
;                 f32x4 aa = w2a * ca + ba, ab = w2b * cb_ + bb;
; #pragma unroll
;                 for (int c = 0; c < 4; ++c) { aa[c] = __builtin_fmaf(w1a[c], dpp_shr1(ca[c]), aa[c]); ab[c] = __builtin_fmaf(w1b[c], dpp_shr1(cb_[c]), ab[c]);
;                     aa[c] = __builtin_fmaf(w0a[c], dpp_shr2(ca[c]), aa[c]); ab[c] = __builtin_fmaf(w0b[c], dpp_shr2(cb_[c]), ab[c]); }
;                 if (m == 0) {
;                     if (ai == 1 || wr == 1) { const int sw = ((ai == 1 && wr == 0) ? 4 : 0) + wc, sai = (ai == 1 && wr == 1) ? 1 : 0;
;                         const PG8_LAS f32x4* xp = (const PG8_LAS f32x4*)(X + ((sw * 2 + sai) * 2) * 32 + fq * 8); const f32x4 h0a = xp[0], h0b = xp[1], h1a = xp[8], h1b = xp[9];
;                         aa += w1a * (h1a * m0) + w0a * (h0a * m0 + h1a * m1); ab += w1b * (h1b * m0) + w0b * (h0b * m0 + h1b * m1); }
;                 } else {
; #pragma unroll
;                     for (int c = 0; c < 4; ++c) { aa[c] = __builtin_fmaf(w1a[c], dpp_shl15(pa[c]), aa[c]); ab[c] = __builtin_fmaf(w1b[c], dpp_shl15(pb[c]), ab[c]);
;                         aa[c] = __builtin_fmaf(w0a[c], dpp_shl14(pa[c]), aa[c]); ab[c] = __builtin_fmaf(w0b[c], dpp_shl14(pb[c]), ab[c]); }
;                 }
;                 const f32x4 ga = acc[ai][1][m][0] * rs, gb = acc[ai][1][m][1] * rs;
;                 f32x4 ea = aa * -1.4426950408889634f, eb = ab * -1.4426950408889634f;
; #pragma unroll
;                 for (int c = 0; c < 4; ++c) { ea[c] = __builtin_amdgcn_exp2f(ea[c]); eb[c] = __builtin_amdgcn_exp2f(eb[c]); }
;                 ea = ea + 1.0f; eb = eb + 1.0f;
; #pragma unroll
;                 for (int c = 0; c < 4; ++c) { ea[c] = __builtin_amdgcn_rcpf(ea[c]); eb[c] = __builtin_amdgcn_rcpf(eb[c]); }
;                 const f32x4 oa = (aa * ga) * ea, ob = (ab * gb) * eb;
;                 u32x4 w; w.x = cvt_pk_bf16(oa[0], oa[1]); w.y = cvt_pk_bf16(oa[2], oa[3]); w.z = cvt_pk_bf16(ob[0], ob[1]); w.w = cvt_pk_bf16(ob[2], ob[3]);
;                 *(u32x4*)(act + (size_t)row * FF + col) = w;
	v_pk_mul_f32 v[56:57], v[56:57], v[170:171] op_sel_hi:[1,0]
	v_pk_mul_f32 v[50:51], v[50:51], v[170:171] op_sel_hi:[1,0]
	v_pk_mul_f32 v[52:53], v[52:53], v[170:171] op_sel_hi:[1,0]
	v_fmac_f32_dpp v236, v62, v114 row_shr:1 row_mask:0xf bank_mask:0xf bound_ctrl:1
	v_fmac_f32_dpp v237, v63, v115 row_shr:1 row_mask:0xf bank_mask:0xf bound_ctrl:1
	v_fmac_f32_dpp v238, v64, v116 row_shr:1 row_mask:0xf bank_mask:0xf bound_ctrl:1
	v_fmac_f32_dpp v239, v65, v117 row_shr:1 row_mask:0xf bank_mask:0xf bound_ctrl:1
	v_fmac_f32_dpp v240, v58, v118 row_shr:1 row_mask:0xf bank_mask:0xf bound_ctrl:1
	v_fmac_f32_dpp v241, v59, v119 row_shr:1 row_mask:0xf bank_mask:0xf bound_ctrl:1
	v_fmac_f32_dpp v242, v60, v120 row_shr:1 row_mask:0xf bank_mask:0xf bound_ctrl:1
	v_fmac_f32_dpp v243, v61, v121 row_shr:1 row_mask:0xf bank_mask:0xf bound_ctrl:1
	v_fmac_f32_dpp v236, v62, v106 row_shr:2 row_mask:0xf bank_mask:0xf bound_ctrl:1
	v_fmac_f32_dpp v237, v63, v107 row_shr:2 row_mask:0xf bank_mask:0xf bound_ctrl:1
	v_fmac_f32_dpp v238, v64, v108 row_shr:2 row_mask:0xf bank_mask:0xf bound_ctrl:1
	v_fmac_f32_dpp v239, v65, v109 row_shr:2 row_mask:0xf bank_mask:0xf bound_ctrl:1
	v_fmac_f32_dpp v240, v58, v110 row_shr:2 row_mask:0xf bank_mask:0xf bound_ctrl:1
	v_fmac_f32_dpp v241, v59, v111 row_shr:2 row_mask:0xf bank_mask:0xf bound_ctrl:1
	v_fmac_f32_dpp v242, v60, v112 row_shr:2 row_mask:0xf bank_mask:0xf bound_ctrl:1
	v_fmac_f32_dpp v243, v61, v113 row_shr:2 row_mask:0xf bank_mask:0xf bound_ctrl:1
	v_cmp_eq_u32_e64 s[44:45], 0, v1
	v_cmp_eq_u32_e64 s[46:47], 1, v1
	s_waitcnt lgkmcnt(0)
	s_mov_b64 exec, s[44:45]
	v_pk_fma_f32 v[236:237], v[114:115], v[200:201], v[236:237]
	v_pk_fma_f32 v[238:239], v[116:117], v[202:203], v[238:239]
	v_pk_fma_f32 v[240:241], v[118:119], v[204:205], v[240:241]
	v_pk_fma_f32 v[242:243], v[120:121], v[206:207], v[242:243]
	v_pk_fma_f32 v[236:237], v[106:107], v[192:193], v[236:237]
	v_pk_fma_f32 v[238:239], v[108:109], v[194:195], v[238:239]
	v_pk_fma_f32 v[240:241], v[110:111], v[196:197], v[240:241]
	v_pk_fma_f32 v[242:243], v[112:113], v[198:199], v[242:243]
	s_mov_b64 exec, s[46:47]
	v_pk_fma_f32 v[236:237], v[106:107], v[200:201], v[236:237]
	v_pk_fma_f32 v[238:239], v[108:109], v[202:203], v[238:239]
	v_pk_fma_f32 v[240:241], v[110:111], v[204:205], v[240:241]
	v_pk_fma_f32 v[242:243], v[112:113], v[206:207], v[242:243]
	s_mov_b64 exec, -1
	v_pk_mul_f32 v[244:245], v[236:237], s[92:93] op_sel_hi:[1,0]
	v_pk_mul_f32 v[246:247], v[238:239], s[92:93] op_sel_hi:[1,0]
	v_pk_mul_f32 v[248:249], v[240:241], s[92:93] op_sel_hi:[1,0]
	v_pk_mul_f32 v[250:251], v[242:243], s[92:93] op_sel_hi:[1,0]
	v_exp_f32_e32 v244, v244
	v_exp_f32_e32 v245, v245
	v_exp_f32_e32 v246, v246
	v_exp_f32_e32 v247, v247
	v_exp_f32_e32 v248, v248
	v_exp_f32_e32 v249, v249
	v_exp_f32_e32 v250, v250
	v_exp_f32_e32 v251, v251
	v_pk_mul_f32 v[236:237], v[236:237], v[54:55]
	v_pk_mul_f32 v[238:239], v[238:239], v[56:57]
	v_pk_mul_f32 v[240:241], v[240:241], v[50:51]
	v_pk_mul_f32 v[242:243], v[242:243], v[52:53]
	v_pk_add_f32 v[244:245], v[244:245], 1.0 op_sel_hi:[1,0]
	v_pk_add_f32 v[246:247], v[246:247], 1.0 op_sel_hi:[1,0]
	v_pk_add_f32 v[248:249], v[248:249], 1.0 op_sel_hi:[1,0]
	v_pk_add_f32 v[250:251], v[250:251], 1.0 op_sel_hi:[1,0]
	v_rcp_f32_e32 v244, v244
	v_rcp_f32_e32 v245, v245
	v_rcp_f32_e32 v246, v246
	v_rcp_f32_e32 v247, v247
	v_rcp_f32_e32 v248, v248
	v_rcp_f32_e32 v249, v249
	v_rcp_f32_e32 v250, v250
	v_rcp_f32_e32 v251, v251
	s_nop 0
	v_pk_mul_f32 v[236:237], v[236:237], v[244:245]
	v_pk_mul_f32 v[238:239], v[238:239], v[246:247]
	v_pk_mul_f32 v[240:241], v[240:241], v[248:249]
	v_pk_mul_f32 v[242:243], v[242:243], v[250:251]
	v_cvt_pk_bf16_f32 v216, v236, v237
	v_cvt_pk_bf16_f32 v217, v238, v239
	v_cvt_pk_bf16_f32 v218, v240, v241
	v_cvt_pk_bf16_f32 v219, v242, v243
	global_store_dwordx4 v[220:221], v[216:219], off sc1
	v_lshl_add_u64 v[220:221], v[220:221], 0, s[100:101]
	v_pk_mul_f32 v[46:47], v[46:47], v[172:173] op_sel_hi:[1,0]
	v_pk_mul_f32 v[48:49], v[48:49], v[172:173] op_sel_hi:[1,0]
	v_pk_mul_f32 v[42:43], v[42:43], v[172:173] op_sel_hi:[1,0]
	v_pk_mul_f32 v[44:45], v[44:45], v[172:173] op_sel_hi:[1,0]
	v_pk_fma_f32 v[236:237], v[122:123], v[46:47], v[130:131]
	v_pk_fma_f32 v[238:239], v[124:125], v[48:49], v[132:133]
	v_pk_fma_f32 v[240:241], v[126:127], v[42:43], v[134:135]
	v_pk_fma_f32 v[242:243], v[128:129], v[44:45], v[136:137]
	v_pk_mul_f32 v[38:39], v[38:39], v[172:173] op_sel_hi:[1,0]
	v_pk_mul_f32 v[40:41], v[40:41], v[172:173] op_sel_hi:[1,0]
	v_pk_mul_f32 v[34:35], v[34:35], v[172:173] op_sel_hi:[1,0]
	v_pk_mul_f32 v[36:37], v[36:37], v[172:173] op_sel_hi:[1,0]
	v_fmac_f32_dpp v236, v46, v114 row_shr:1 row_mask:0xf bank_mask:0xf bound_ctrl:1
	v_fmac_f32_dpp v237, v47, v115 row_shr:1 row_mask:0xf bank_mask:0xf bound_ctrl:1
	v_fmac_f32_dpp v238, v48, v116 row_shr:1 row_mask:0xf bank_mask:0xf bound_ctrl:1
	v_fmac_f32_dpp v239, v49, v117 row_shr:1 row_mask:0xf bank_mask:0xf bound_ctrl:1
	v_fmac_f32_dpp v240, v42, v118 row_shr:1 row_mask:0xf bank_mask:0xf bound_ctrl:1
	v_fmac_f32_dpp v241, v43, v119 row_shr:1 row_mask:0xf bank_mask:0xf bound_ctrl:1
	v_fmac_f32_dpp v242, v44, v120 row_shr:1 row_mask:0xf bank_mask:0xf bound_ctrl:1
	v_fmac_f32_dpp v243, v45, v121 row_shr:1 row_mask:0xf bank_mask:0xf bound_ctrl:1
	v_fmac_f32_dpp v236, v46, v106 row_shr:2 row_mask:0xf bank_mask:0xf bound_ctrl:1
	v_fmac_f32_dpp v237, v47, v107 row_shr:2 row_mask:0xf bank_mask:0xf bound_ctrl:1
	v_fmac_f32_dpp v238, v48, v108 row_shr:2 row_mask:0xf bank_mask:0xf bound_ctrl:1
	v_fmac_f32_dpp v239, v49, v109 row_shr:2 row_mask:0xf bank_mask:0xf bound_ctrl:1
;     __device__ __forceinline__ void operator()(const f32x4 (&acc)[2][2][4][2], const Unit& u, int wr, int wc, int fr, int fq) const {
;     ...
;             for (int m = 0; m < 4; ++m) {
;                 const int row = row0 + ai * HALF + m * 16; const float rs = rsv[m];
;                 const f32x4 ca = acc[ai][0][m][0] * rs, cb_ = acc[ai][0][m][1] * rs;
;                 f32x4 aa = w2a * ca + ba, ab = w2b * cb_ + bb;
; #pragma unroll
;                 for (int c = 0; c < 4; ++c) { aa[c] = __builtin_fmaf(w1a[c], dpp_shr1(ca[c]), aa[c]); ab[c] = __builtin_fmaf(w1b[c], dpp_shr1(cb_[c]), ab[c]);
;                     aa[c] = __builtin_fmaf(w0a[c], dpp_shr2(ca[c]), aa[c]); ab[c] = __builtin_fmaf(w0b[c], dpp_shr2(cb_[c]), ab[c]); }
;                 if (m == 0) {
;                     if (ai == 1 || wr == 1) { const int sw = ((ai == 1 && wr == 0) ? 4 : 0) + wc, sai = (ai == 1 && wr == 1) ? 1 : 0;
;                         const PG8_LAS f32x4* xp = (const PG8_LAS f32x4*)(X + ((sw * 2 + sai) * 2) * 32 + fq * 8); const f32x4 h0a = xp[0], h0b = xp[1], h1a = xp[8], h1b = xp[9];
;                         aa += w1a * (h1a * m0) + w0a * (h0a * m0 + h1a * m1); ab += w1b * (h1b * m0) + w0b * (h0b * m0 + h1b * m1); }
;                 } else {
; #pragma unroll
;                     for (int c = 0; c < 4; ++c) { aa[c] = __builtin_fmaf(w1a[c], dpp_shl15(pa[c]), aa[c]); ab[c] = __builtin_fmaf(w1b[c], dpp_shl15(pb[c]), ab[c]);
;                         aa[c] = __builtin_fmaf(w0a[c], dpp_shl14(pa[c]), aa[c]); ab[c] = __builtin_fmaf(w0b[c], dpp_shl14(pb[c]), ab[c]); }
;                 }
;                 const f32x4 ga = acc[ai][1][m][0] * rs, gb = acc[ai][1][m][1] * rs;
;                 f32x4 ea = aa * -1.4426950408889634f, eb = ab * -1.4426950408889634f;
; #pragma unroll
;                 for (int c = 0; c < 4; ++c) { ea[c] = __builtin_amdgcn_exp2f(ea[c]); eb[c] = __builtin_amdgcn_exp2f(eb[c]); }
;                 ea = ea + 1.0f; eb = eb + 1.0f;
; #pragma unroll
;                 for (int c = 0; c < 4; ++c) { ea[c] = __builtin_amdgcn_rcpf(ea[c]); eb[c] = __builtin_amdgcn_rcpf(eb[c]); }
;                 const f32x4 oa = (aa * ga) * ea, ob = (ab * gb) * eb;
;                 u32x4 w; w.x = cvt_pk_bf16(oa[0], oa[1]); w.y = cvt_pk_bf16(oa[2], oa[3]); w.z = cvt_pk_bf16(ob[0], ob[1]); w.w = cvt_pk_bf16(ob[2], ob[3]);
;                 *(u32x4*)(act + (size_t)row * FF + col) = w;
	v_fmac_f32_dpp v240, v42, v110 row_shr:2 row_mask:0xf bank_mask:0xf bound_ctrl:1
	v_fmac_f32_dpp v241, v43, v111 row_shr:2 row_mask:0xf bank_mask:0xf bound_ctrl:1
	v_fmac_f32_dpp v242, v44, v112 row_shr:2 row_mask:0xf bank_mask:0xf bound_ctrl:1
	v_fmac_f32_dpp v243, v45, v113 row_shr:2 row_mask:0xf bank_mask:0xf bound_ctrl:1
	v_fmac_f32_dpp v236, v62, v114 row_shl:15 row_mask:0xf bank_mask:0xf bound_ctrl:1
	v_fmac_f32_dpp v237, v63, v115 row_shl:15 row_mask:0xf bank_mask:0xf bound_ctrl:1
	v_fmac_f32_dpp v238, v64, v116 row_shl:15 row_mask:0xf bank_mask:0xf bound_ctrl:1
	v_fmac_f32_dpp v239, v65, v117 row_shl:15 row_mask:0xf bank_mask:0xf bound_ctrl:1
	v_fmac_f32_dpp v240, v58, v118 row_shl:15 row_mask:0xf bank_mask:0xf bound_ctrl:1
	v_fmac_f32_dpp v241, v59, v119 row_shl:15 row_mask:0xf bank_mask:0xf bound_ctrl:1
	v_fmac_f32_dpp v242, v60, v120 row_shl:15 row_mask:0xf bank_mask:0xf bound_ctrl:1
	v_fmac_f32_dpp v243, v61, v121 row_shl:15 row_mask:0xf bank_mask:0xf bound_ctrl:1
	v_fmac_f32_dpp v236, v62, v106 row_shl:14 row_mask:0xf bank_mask:0xf bound_ctrl:1
	v_fmac_f32_dpp v237, v63, v107 row_shl:14 row_mask:0xf bank_mask:0xf bound_ctrl:1
	v_fmac_f32_dpp v238, v64, v108 row_shl:14 row_mask:0xf bank_mask:0xf bound_ctrl:1
	v_fmac_f32_dpp v239, v65, v109 row_shl:14 row_mask:0xf bank_mask:0xf bound_ctrl:1
	v_fmac_f32_dpp v240, v58, v110 row_shl:14 row_mask:0xf bank_mask:0xf bound_ctrl:1
	v_fmac_f32_dpp v241, v59, v111 row_shl:14 row_mask:0xf bank_mask:0xf bound_ctrl:1
	v_fmac_f32_dpp v242, v60, v112 row_shl:14 row_mask:0xf bank_mask:0xf bound_ctrl:1
	v_fmac_f32_dpp v243, v61, v113 row_shl:14 row_mask:0xf bank_mask:0xf bound_ctrl:1
	v_pk_mul_f32 v[244:245], v[236:237], s[92:93] op_sel_hi:[1,0]
	v_pk_mul_f32 v[246:247], v[238:239], s[92:93] op_sel_hi:[1,0]
	v_pk_mul_f32 v[248:249], v[240:241], s[92:93] op_sel_hi:[1,0]
	v_pk_mul_f32 v[250:251], v[242:243], s[92:93] op_sel_hi:[1,0]
	v_exp_f32_e32 v244, v244
	v_exp_f32_e32 v245, v245
	v_exp_f32_e32 v246, v246
	v_exp_f32_e32 v247, v247
	v_exp_f32_e32 v248, v248
	v_exp_f32_e32 v249, v249
	v_exp_f32_e32 v250, v250
	v_exp_f32_e32 v251, v251
	v_pk_mul_f32 v[236:237], v[236:237], v[38:39]
	v_pk_mul_f32 v[238:239], v[238:239], v[40:41]
	v_pk_mul_f32 v[240:241], v[240:241], v[34:35]
	v_pk_mul_f32 v[242:243], v[242:243], v[36:37]
	v_pk_add_f32 v[244:245], v[244:245], 1.0 op_sel_hi:[1,0]
	v_pk_add_f32 v[246:247], v[246:247], 1.0 op_sel_hi:[1,0]
	v_pk_add_f32 v[248:249], v[248:249], 1.0 op_sel_hi:[1,0]
	v_pk_add_f32 v[250:251], v[250:251], 1.0 op_sel_hi:[1,0]
	v_rcp_f32_e32 v244, v244
	v_rcp_f32_e32 v245, v245
	v_rcp_f32_e32 v246, v246
	v_rcp_f32_e32 v247, v247
	v_rcp_f32_e32 v248, v248
	v_rcp_f32_e32 v249, v249
	v_rcp_f32_e32 v250, v250
	v_rcp_f32_e32 v251, v251
	s_nop 0
	v_pk_mul_f32 v[236:237], v[236:237], v[244:245]
	v_pk_mul_f32 v[238:239], v[238:239], v[246:247]
	v_pk_mul_f32 v[240:241], v[240:241], v[248:249]
	v_pk_mul_f32 v[242:243], v[242:243], v[250:251]
	v_cvt_pk_bf16_f32 v216, v236, v237
	v_cvt_pk_bf16_f32 v217, v238, v239
	v_cvt_pk_bf16_f32 v218, v240, v241
	v_cvt_pk_bf16_f32 v219, v242, v243
	global_store_dwordx4 v[220:221], v[216:219], off sc1
	v_lshl_add_u64 v[220:221], v[220:221], 0, s[100:101]
	v_pk_mul_f32 v[30:31], v[30:31], v[232:233] op_sel_hi:[1,0]
	v_pk_mul_f32 v[32:33], v[32:33], v[232:233] op_sel_hi:[1,0]
	v_pk_mul_f32 v[26:27], v[26:27], v[232:233] op_sel_hi:[1,0]
	v_pk_mul_f32 v[28:29], v[28:29], v[232:233] op_sel_hi:[1,0]
	v_pk_fma_f32 v[236:237], v[122:123], v[30:31], v[130:131]
	v_pk_fma_f32 v[238:239], v[124:125], v[32:33], v[132:133]
	v_pk_fma_f32 v[240:241], v[126:127], v[26:27], v[134:135]
	v_pk_fma_f32 v[242:243], v[128:129], v[28:29], v[136:137]
	v_pk_mul_f32 v[22:23], v[22:23], v[232:233] op_sel_hi:[1,0]
	v_pk_mul_f32 v[24:25], v[24:25], v[232:233] op_sel_hi:[1,0]
	v_pk_mul_f32 v[18:19], v[18:19], v[232:233] op_sel_hi:[1,0]
	v_pk_mul_f32 v[20:21], v[20:21], v[232:233] op_sel_hi:[1,0]
	v_fmac_f32_dpp v236, v30, v114 row_shr:1 row_mask:0xf bank_mask:0xf bound_ctrl:1
	v_fmac_f32_dpp v237, v31, v115 row_shr:1 row_mask:0xf bank_mask:0xf bound_ctrl:1
	v_fmac_f32_dpp v238, v32, v116 row_shr:1 row_mask:0xf bank_mask:0xf bound_ctrl:1
	v_fmac_f32_dpp v239, v33, v117 row_shr:1 row_mask:0xf bank_mask:0xf bound_ctrl:1
	v_fmac_f32_dpp v240, v26, v118 row_shr:1 row_mask:0xf bank_mask:0xf bound_ctrl:1
	v_fmac_f32_dpp v241, v27, v119 row_shr:1 row_mask:0xf bank_mask:0xf bound_ctrl:1
	v_fmac_f32_dpp v242, v28, v120 row_shr:1 row_mask:0xf bank_mask:0xf bound_ctrl:1
	v_fmac_f32_dpp v243, v29, v121 row_shr:1 row_mask:0xf bank_mask:0xf bound_ctrl:1
	v_fmac_f32_dpp v236, v30, v106 row_shr:2 row_mask:0xf bank_mask:0xf bound_ctrl:1
	v_fmac_f32_dpp v237, v31, v107 row_shr:2 row_mask:0xf bank_mask:0xf bound_ctrl:1
	v_fmac_f32_dpp v238, v32, v108 row_shr:2 row_mask:0xf bank_mask:0xf bound_ctrl:1
	v_fmac_f32_dpp v239, v33, v109 row_shr:2 row_mask:0xf bank_mask:0xf bound_ctrl:1
	v_fmac_f32_dpp v240, v26, v110 row_shr:2 row_mask:0xf bank_mask:0xf bound_ctrl:1
	v_fmac_f32_dpp v241, v27, v111 row_shr:2 row_mask:0xf bank_mask:0xf bound_ctrl:1
	v_fmac_f32_dpp v242, v28, v112 row_shr:2 row_mask:0xf bank_mask:0xf bound_ctrl:1
	v_fmac_f32_dpp v243, v29, v113 row_shr:2 row_mask:0xf bank_mask:0xf bound_ctrl:1
	v_fmac_f32_dpp v236, v46, v114 row_shl:15 row_mask:0xf bank_mask:0xf bound_ctrl:1
	v_fmac_f32_dpp v237, v47, v115 row_shl:15 row_mask:0xf bank_mask:0xf bound_ctrl:1
	v_fmac_f32_dpp v238, v48, v116 row_shl:15 row_mask:0xf bank_mask:0xf bound_ctrl:1
	v_fmac_f32_dpp v239, v49, v117 row_shl:15 row_mask:0xf bank_mask:0xf bound_ctrl:1
	v_fmac_f32_dpp v240, v42, v118 row_shl:15 row_mask:0xf bank_mask:0xf bound_ctrl:1
;     __device__ __forceinline__ void operator()(const f32x4 (&acc)[2][2][4][2], const Unit& u, int wr, int wc, int fr, int fq) const {
;     ...
;             for (int m = 0; m < 4; ++m) {
;                 const int row = row0 + ai * HALF + m * 16; const float rs = rsv[m];
;                 const f32x4 ca = acc[ai][0][m][0] * rs, cb_ = acc[ai][0][m][1] * rs;
;                 f32x4 aa = w2a * ca + ba, ab = w2b * cb_ + bb;
; #pragma unroll
;                 for (int c = 0; c < 4; ++c) { aa[c] = __builtin_fmaf(w1a[c], dpp_shr1(ca[c]), aa[c]); ab[c] = __builtin_fmaf(w1b[c], dpp_shr1(cb_[c]), ab[c]);
;                     aa[c] = __builtin_fmaf(w0a[c], dpp_shr2(ca[c]), aa[c]); ab[c] = __builtin_fmaf(w0b[c], dpp_shr2(cb_[c]), ab[c]); }
;                 if (m == 0) {
;                     if (ai == 1 || wr == 1) { const int sw = ((ai == 1 && wr == 0) ? 4 : 0) + wc, sai = (ai == 1 && wr == 1) ? 1 : 0;
;                         const PG8_LAS f32x4* xp = (const PG8_LAS f32x4*)(X + ((sw * 2 + sai) * 2) * 32 + fq * 8); const f32x4 h0a = xp[0], h0b = xp[1], h1a = xp[8], h1b = xp[9];
;                         aa += w1a * (h1a * m0) + w0a * (h0a * m0 + h1a * m1); ab += w1b * (h1b * m0) + w0b * (h0b * m0 + h1b * m1); }
;                 } else {
; #pragma unroll
;                     for (int c = 0; c < 4; ++c) { aa[c] = __builtin_fmaf(w1a[c], dpp_shl15(pa[c]), aa[c]); ab[c] = __builtin_fmaf(w1b[c], dpp_shl15(pb[c]), ab[c]);
;                         aa[c] = __builtin_fmaf(w0a[c], dpp_shl14(pa[c]), aa[c]); ab[c] = __builtin_fmaf(w0b[c], dpp_shl14(pb[c]), ab[c]); }
;                 }
;                 const f32x4 ga = acc[ai][1][m][0] * rs, gb = acc[ai][1][m][1] * rs;
;                 f32x4 ea = aa * -1.4426950408889634f, eb = ab * -1.4426950408889634f;
; #pragma unroll
;                 for (int c = 0; c < 4; ++c) { ea[c] = __builtin_amdgcn_exp2f(ea[c]); eb[c] = __builtin_amdgcn_exp2f(eb[c]); }
;                 ea = ea + 1.0f; eb = eb + 1.0f;
; #pragma unroll
;                 for (int c = 0; c < 4; ++c) { ea[c] = __builtin_amdgcn_rcpf(ea[c]); eb[c] = __builtin_amdgcn_rcpf(eb[c]); }
;                 const f32x4 oa = (aa * ga) * ea, ob = (ab * gb) * eb;
;                 u32x4 w; w.x = cvt_pk_bf16(oa[0], oa[1]); w.y = cvt_pk_bf16(oa[2], oa[3]); w.z = cvt_pk_bf16(ob[0], ob[1]); w.w = cvt_pk_bf16(ob[2], ob[3]);
;                 *(u32x4*)(act + (size_t)row * FF + col) = w;
	v_fmac_f32_dpp v241, v43, v119 row_shl:15 row_mask:0xf bank_mask:0xf bound_ctrl:1
	v_fmac_f32_dpp v242, v44, v120 row_shl:15 row_mask:0xf bank_mask:0xf bound_ctrl:1
	v_fmac_f32_dpp v243, v45, v121 row_shl:15 row_mask:0xf bank_mask:0xf bound_ctrl:1
	v_fmac_f32_dpp v236, v46, v106 row_shl:14 row_mask:0xf bank_mask:0xf bound_ctrl:1
	v_fmac_f32_dpp v237, v47, v107 row_shl:14 row_mask:0xf bank_mask:0xf bound_ctrl:1
	v_fmac_f32_dpp v238, v48, v108 row_shl:14 row_mask:0xf bank_mask:0xf bound_ctrl:1
	v_fmac_f32_dpp v239, v49, v109 row_shl:14 row_mask:0xf bank_mask:0xf bound_ctrl:1
	v_fmac_f32_dpp v240, v42, v110 row_shl:14 row_mask:0xf bank_mask:0xf bound_ctrl:1
	v_fmac_f32_dpp v241, v43, v111 row_shl:14 row_mask:0xf bank_mask:0xf bound_ctrl:1
	v_fmac_f32_dpp v242, v44, v112 row_shl:14 row_mask:0xf bank_mask:0xf bound_ctrl:1
	v_fmac_f32_dpp v243, v45, v113 row_shl:14 row_mask:0xf bank_mask:0xf bound_ctrl:1
	v_pk_mul_f32 v[244:245], v[236:237], s[92:93] op_sel_hi:[1,0]
	v_pk_mul_f32 v[246:247], v[238:239], s[92:93] op_sel_hi:[1,0]
	v_pk_mul_f32 v[248:249], v[240:241], s[92:93] op_sel_hi:[1,0]
	v_pk_mul_f32 v[250:251], v[242:243], s[92:93] op_sel_hi:[1,0]
	v_exp_f32_e32 v244, v244
	v_exp_f32_e32 v245, v245
	v_exp_f32_e32 v246, v246
	v_exp_f32_e32 v247, v247
	v_exp_f32_e32 v248, v248
	v_exp_f32_e32 v249, v249
	v_exp_f32_e32 v250, v250
	v_exp_f32_e32 v251, v251
	v_pk_mul_f32 v[236:237], v[236:237], v[22:23]
	v_pk_mul_f32 v[238:239], v[238:239], v[24:25]
	v_pk_mul_f32 v[240:241], v[240:241], v[18:19]
	v_pk_mul_f32 v[242:243], v[242:243], v[20:21]
	v_pk_add_f32 v[244:245], v[244:245], 1.0 op_sel_hi:[1,0]
	v_pk_add_f32 v[246:247], v[246:247], 1.0 op_sel_hi:[1,0]
	v_pk_add_f32 v[248:249], v[248:249], 1.0 op_sel_hi:[1,0]
	v_pk_add_f32 v[250:251], v[250:251], 1.0 op_sel_hi:[1,0]
	v_rcp_f32_e32 v244, v244
	v_rcp_f32_e32 v245, v245
	v_rcp_f32_e32 v246, v246
	v_rcp_f32_e32 v247, v247
	v_rcp_f32_e32 v248, v248
	v_rcp_f32_e32 v249, v249
	v_rcp_f32_e32 v250, v250
	v_rcp_f32_e32 v251, v251
	s_nop 0
	v_pk_mul_f32 v[236:237], v[236:237], v[244:245]
	v_pk_mul_f32 v[238:239], v[238:239], v[246:247]
	v_pk_mul_f32 v[240:241], v[240:241], v[248:249]
	v_pk_mul_f32 v[242:243], v[242:243], v[250:251]
	v_cvt_pk_bf16_f32 v216, v236, v237
	v_cvt_pk_bf16_f32 v217, v238, v239
	v_cvt_pk_bf16_f32 v218, v240, v241
	v_cvt_pk_bf16_f32 v219, v242, v243
	global_store_dwordx4 v[220:221], v[216:219], off sc1
	v_lshl_add_u64 v[220:221], v[220:221], 0, s[100:101]
	v_pk_fma_f32 v[236:237], v[122:123], v[14:15], v[130:131]
	v_pk_fma_f32 v[238:239], v[124:125], v[16:17], v[132:133]
	v_pk_fma_f32 v[240:241], v[126:127], v[10:11], v[134:135]
	v_pk_fma_f32 v[242:243], v[128:129], v[12:13], v[136:137]
	v_pk_mul_f32 v[6:7], v[6:7], v[234:235] op_sel_hi:[1,0]
	v_pk_mul_f32 v[8:9], v[8:9], v[234:235] op_sel_hi:[1,0]
	v_pk_mul_f32 v[2:3], v[2:3], v[234:235] op_sel_hi:[1,0]
	v_pk_mul_f32 v[4:5], v[4:5], v[234:235] op_sel_hi:[1,0]
	v_fmac_f32_dpp v236, v14, v114 row_shr:1 row_mask:0xf bank_mask:0xf bound_ctrl:1
	v_fmac_f32_dpp v237, v15, v115 row_shr:1 row_mask:0xf bank_mask:0xf bound_ctrl:1
	v_fmac_f32_dpp v238, v16, v116 row_shr:1 row_mask:0xf bank_mask:0xf bound_ctrl:1
	v_fmac_f32_dpp v239, v17, v117 row_shr:1 row_mask:0xf bank_mask:0xf bound_ctrl:1
	v_fmac_f32_dpp v240, v10, v118 row_shr:1 row_mask:0xf bank_mask:0xf bound_ctrl:1
	v_fmac_f32_dpp v241, v11, v119 row_shr:1 row_mask:0xf bank_mask:0xf bound_ctrl:1
	v_fmac_f32_dpp v242, v12, v120 row_shr:1 row_mask:0xf bank_mask:0xf bound_ctrl:1
	v_fmac_f32_dpp v243, v13, v121 row_shr:1 row_mask:0xf bank_mask:0xf bound_ctrl:1
	v_fmac_f32_dpp v236, v14, v106 row_shr:2 row_mask:0xf bank_mask:0xf bound_ctrl:1
; __device__ __forceinline__ unsigned cvt_pk_bf16(float lo, float hi) { unsigned r; asm volatile("v_cvt_pk_bf16_f32 %0, %1, %2" : "=v"(r) : "v"(lo), "v"(hi)); return r; }
; #define PG8_BAR __builtin_amdgcn_s_barrier()
;     __device__ __forceinline__ void operator()(const f32x4 (&acc)[2][2][4][2], const Unit& u, int wr, int wc, int fr, int fq) const {
;     ...
;                 const f32x4 ga = acc[ai][1][m][0] * rs, gb = acc[ai][1][m][1] * rs;
;                 f32x4 ea = aa * -1.4426950408889634f, eb = ab * -1.4426950408889634f;
; #pragma unroll
;                 for (int c = 0; c < 4; ++c) { ea[c] = __builtin_amdgcn_exp2f(ea[c]); eb[c] = __builtin_amdgcn_exp2f(eb[c]); }
;                 ea = ea + 1.0f; eb = eb + 1.0f;
; #pragma unroll
;                 for (int c = 0; c < 4; ++c) { ea[c] = __builtin_amdgcn_rcpf(ea[c]); eb[c] = __builtin_amdgcn_rcpf(eb[c]); }
;                 const f32x4 oa = (aa * ga) * ea, ob = (ab * gb) * eb;
;                 u32x4 w; w.x = cvt_pk_bf16(oa[0], oa[1]); w.y = cvt_pk_bf16(oa[2], oa[3]); w.z = cvt_pk_bf16(ob[0], ob[1]); w.w = cvt_pk_bf16(ob[2], ob[3]);
;                 *(u32x4*)(act + (size_t)row * FF + col) = w;
; template <class Epi, class Sched, bool ALIGN_EPI = false, bool SP2 = false>
; __device__ __forceinline__ void gemm_phase(PG8_LAS unsigned char* lds, const Gemm g, const Sched& S, const Epi& E) {
;     ...
;         if constexpr (!Epi::AFTER_DRAIN) { E(acc, cur, wr, wc, fr, fq); S.done(cur); }
;         if (!has_next) break;
; #pragma unroll
;         for (int a = 0; a < 2; ++a)
; #pragma unroll
;             for (int b = 0; b < 2; ++b)
; #pragma unroll
;                 for (int m = 0; m < 4; ++m)
; #pragma unroll
;                     for (int n = 0; n < 2; ++n) acc[a][b][m][n] = (f32x4){0.f, 0.f, 0.f, 0.f};
;         cur = nxt; cA = nA; cB = nB; ++ui;
;         if constexpr (ALIGN_EPI) { if (wr == 1) PG8_BAR; }
	v_fmac_f32_dpp v237, v15, v107 row_shr:2 row_mask:0xf bank_mask:0xf bound_ctrl:1
	v_fmac_f32_dpp v238, v16, v108 row_shr:2 row_mask:0xf bank_mask:0xf bound_ctrl:1
	v_fmac_f32_dpp v239, v17, v109 row_shr:2 row_mask:0xf bank_mask:0xf bound_ctrl:1
	v_fmac_f32_dpp v240, v10, v110 row_shr:2 row_mask:0xf bank_mask:0xf bound_ctrl:1
	v_fmac_f32_dpp v241, v11, v111 row_shr:2 row_mask:0xf bank_mask:0xf bound_ctrl:1
	v_fmac_f32_dpp v242, v12, v112 row_shr:2 row_mask:0xf bank_mask:0xf bound_ctrl:1
	v_fmac_f32_dpp v243, v13, v113 row_shr:2 row_mask:0xf bank_mask:0xf bound_ctrl:1
	v_fmac_f32_dpp v236, v30, v114 row_shl:15 row_mask:0xf bank_mask:0xf bound_ctrl:1
	v_fmac_f32_dpp v237, v31, v115 row_shl:15 row_mask:0xf bank_mask:0xf bound_ctrl:1
	v_fmac_f32_dpp v238, v32, v116 row_shl:15 row_mask:0xf bank_mask:0xf bound_ctrl:1
	v_fmac_f32_dpp v239, v33, v117 row_shl:15 row_mask:0xf bank_mask:0xf bound_ctrl:1
	v_fmac_f32_dpp v240, v26, v118 row_shl:15 row_mask:0xf bank_mask:0xf bound_ctrl:1
	v_fmac_f32_dpp v241, v27, v119 row_shl:15 row_mask:0xf bank_mask:0xf bound_ctrl:1
	v_fmac_f32_dpp v242, v28, v120 row_shl:15 row_mask:0xf bank_mask:0xf bound_ctrl:1
	v_fmac_f32_dpp v243, v29, v121 row_shl:15 row_mask:0xf bank_mask:0xf bound_ctrl:1
	v_fmac_f32_dpp v236, v30, v106 row_shl:14 row_mask:0xf bank_mask:0xf bound_ctrl:1
	v_fmac_f32_dpp v237, v31, v107 row_shl:14 row_mask:0xf bank_mask:0xf bound_ctrl:1
	v_fmac_f32_dpp v238, v32, v108 row_shl:14 row_mask:0xf bank_mask:0xf bound_ctrl:1
	v_fmac_f32_dpp v239, v33, v109 row_shl:14 row_mask:0xf bank_mask:0xf bound_ctrl:1
	v_fmac_f32_dpp v240, v26, v110 row_shl:14 row_mask:0xf bank_mask:0xf bound_ctrl:1
	v_fmac_f32_dpp v241, v27, v111 row_shl:14 row_mask:0xf bank_mask:0xf bound_ctrl:1
	v_fmac_f32_dpp v242, v28, v112 row_shl:14 row_mask:0xf bank_mask:0xf bound_ctrl:1
	v_fmac_f32_dpp v243, v29, v113 row_shl:14 row_mask:0xf bank_mask:0xf bound_ctrl:1
	v_pk_mul_f32 v[244:245], v[236:237], s[92:93] op_sel_hi:[1,0]
	v_pk_mul_f32 v[246:247], v[238:239], s[92:93] op_sel_hi:[1,0]
	v_pk_mul_f32 v[248:249], v[240:241], s[92:93] op_sel_hi:[1,0]
	v_pk_mul_f32 v[250:251], v[242:243], s[92:93] op_sel_hi:[1,0]
	v_exp_f32_e32 v244, v244
	v_exp_f32_e32 v245, v245
	v_exp_f32_e32 v246, v246
	v_exp_f32_e32 v247, v247
	v_exp_f32_e32 v248, v248
	v_exp_f32_e32 v249, v249
	v_exp_f32_e32 v250, v250
	v_exp_f32_e32 v251, v251
	v_pk_mul_f32 v[236:237], v[236:237], v[6:7]
	v_pk_mul_f32 v[238:239], v[238:239], v[8:9]
	v_pk_mul_f32 v[240:241], v[240:241], v[2:3]
	v_pk_mul_f32 v[242:243], v[242:243], v[4:5]
	v_pk_add_f32 v[244:245], v[244:245], 1.0 op_sel_hi:[1,0]
	v_pk_add_f32 v[246:247], v[246:247], 1.0 op_sel_hi:[1,0]
	v_pk_add_f32 v[248:249], v[248:249], 1.0 op_sel_hi:[1,0]
	v_pk_add_f32 v[250:251], v[250:251], 1.0 op_sel_hi:[1,0]
	v_rcp_f32_e32 v244, v244
	v_rcp_f32_e32 v245, v245
	v_rcp_f32_e32 v246, v246
	v_rcp_f32_e32 v247, v247
	v_rcp_f32_e32 v248, v248
	v_rcp_f32_e32 v249, v249
	v_rcp_f32_e32 v250, v250
	v_rcp_f32_e32 v251, v251
	s_nop 0
	v_pk_mul_f32 v[236:237], v[236:237], v[244:245]
	v_pk_mul_f32 v[238:239], v[238:239], v[246:247]
	v_pk_mul_f32 v[240:241], v[240:241], v[248:249]
	v_pk_mul_f32 v[242:243], v[242:243], v[250:251]
	v_cvt_pk_bf16_f32 v216, v236, v237
	v_cvt_pk_bf16_f32 v217, v238, v239
	v_cvt_pk_bf16_f32 v218, v240, v241
	v_cvt_pk_bf16_f32 v219, v242, v243
	global_store_dwordx4 v[220:221], v[216:219], off sc1
	s_mov_b64 s[66:67], 0x8000
	s_andn2_b64 vcc, exec, s[6:7]
	s_mov_b64 s[6:7], -1
	s_not_b64 s[8:9], s[4:5]
	s_cbranch_vccnz .LBB0_1243
	s_mov_b32 s101, 0
	s_and_b64 vcc, exec, s[8:9]
	s_cbranch_vccnz .LBB0_1242
	s_mov_b32 s101, 1
	s_branch .LBB0_1242

; #define PG8_STAGE(bufoff, gbase, voff) do { _Pragma("unroll") for (int _i = 0; _i < 2; ++_i) \
;         __builtin_amdgcn_global_load_lds((const unsigned*)((const char*)(gbase) + (voff)[_i]), (PG8_LAS unsigned*)(lds + (bufoff) + ldsw + _i * 8192), 16, 0, 0); } while (0)
; #define PG8_LDA(dst, b, h) do { _Pragma("unroll") for (int m = 0; m < 4; ++m) _Pragma("unroll") for (int k = 0; k < 2; ++k) dst[m][k] = *(const PG8_LAS bf16x8*)(lds + PG8_SA(b, h) + aoff + m * 2048 + k * 1024); } while (0)
; #define PG8_LDB(dst, b, h) do { _Pragma("unroll") for (int n = 0; n < 2; ++n) _Pragma("unroll") for (int k = 0; k < 2; ++k) dst[n][k] = *(const PG8_LAS bf16x8*)(lds + PG8_SB(b, h) + boff + n * 2048 + k * 1024); } while (0)
; #define PG8_SCHED __builtin_amdgcn_sched_barrier(0)
; template <class Epi, class Sched, bool ALIGN_EPI = false, bool SP2 = false>
; __device__ __forceinline__ void gemm_phase(PG8_LAS unsigned char* lds, const Gemm g, const Sched& S, const Epi& E) {
;     ...
;         const bool has_next = S.next(ui + 1, nxt);
;         const char* nA = has_next ? (const char*)g.A + (size_t)nxt.pm * tstep : cA; const char* nB = has_next ? (const char*)g.Bt + (size_t)nxt.pn * tstep : cB;
;         for (int t = 0; t < nt; t += 2) {
;             const bool last = (t == nt - 2);
;             const char* a1 = cA + (size_t)(t + 1) * kstep;
;             const char* a2 = last ? nA : cA + (size_t)(t + 2) * kstep; const char* b2 = last ? nB : cB + (size_t)(t + 2) * kstep;
;             const char* a3 = a2 + kstep; const char* b3 = b2 + kstep;
;             if (last && has_next) S.a_ready(nxt);
;             if constexpr (SP2) {
;             PG8_LDB(B0, 0, 0); PG8_LDB(B1, 0, 1); PG8_SCHED; PG8_LDA(At, 0, 0); PG8_STAGE(PG8_SA(1, 1), a1 + hstep, voffA);
;     ...
; #pragma unroll
;         for (int a = 0; a < 2; ++a)
; #pragma unroll
;             for (int b = 0; b < 2; ++b)
; #pragma unroll
;                 for (int m = 0; m < 4; ++m)
; #pragma unroll
;                     for (int n = 0; n < 2; ++n) acc[a][b][m][n] = (f32x4){0.f, 0.f, 0.f, 0.f};
.LBB0_1359:
	s_add_u32 s33, s24, 0x100
	s_addc_u32 s49, s25, 0
	s_mov_b32 s50, -2
	s_waitcnt lgkmcnt(0)
	s_cmp_eq_u32 s101, 1
	s_cbranch_scc0 .Ldb5
	s_mov_b32 s101, 0
	s_barrier
.Ldb5:
.LBB0_1360:
	s_add_u32 s8, s22, 0x100
	s_addc_u32 s9, s23, 0
	s_add_i32 s51, 0, 0x10000
	s_cmp_eq_u32 s50, 40
	s_cselect_b32 s27, s19, s9
	s_cselect_b32 s26, s18, s8
	s_cselect_b32 s25, s21, s49
	s_cselect_b32 s24, s20, s33
	s_add_i32 s52, 0, 0x14000
	v_add_u32_e32 v134, s51, v185
	v_add_u32_e32 v170, s52, v185
	ds_read_b128 v[114:117], v134
	ds_read_b128 v[118:121], v134 offset:1024
	ds_read_b128 v[122:125], v134 offset:2048
	ds_read_b128 v[134:137], v134 offset:3072
	ds_read_b128 v[146:149], v170
	ds_read_b128 v[150:153], v170 offset:1024
	ds_read_b128 v[166:169], v170 offset:2048
	ds_read_b128 v[170:173], v170 offset:3072
	v_lshl_add_u64 v[216:217], s[22:23], 0, v[162:163]
	s_add_i32 m0, s35, 0xc000
	ds_read_b128 v[180:183], v186
	ds_read_b128 v[188:191], v186 offset:1024
	ds_read_b128 v[192:195], v186 offset:2048
	ds_read_b128 v[196:199], v186 offset:3072
	ds_read_b128 v[200:203], v186 offset:4096
	ds_read_b128 v[204:207], v186 offset:5120
	ds_read_b128 v[208:211], v186 offset:6144
	ds_read_b128 v[212:215], v186 offset:7168
	global_load_lds_dwordx4 v[216:217], off
	v_lshl_add_u64 v[216:217], s[22:23], 0, v[164:165]
	s_add_i32 m0, s35, 0xe000
	s_nop 0
	global_load_lds_dwordx4 v[216:217], off
	s_cmp_lg_u32 s50, -2
	s_cbranch_scc1 .Lffout_noz
	v_mov_b32_e32 v2, 0
	v_mov_b32_e32 v3, v2
	v_mov_b32_e32 v4, v2
	v_mov_b32_e32 v5, v2
	v_mov_b32_e32 v6, v2
	v_mov_b32_e32 v7, v2
	v_mov_b32_e32 v8, v2
	v_mov_b32_e32 v9, v2
	v_mov_b32_e32 v18, v2
	v_mov_b32_e32 v19, v2
	v_mov_b32_e32 v20, v2
	v_mov_b32_e32 v21, v2
	v_mov_b32_e32 v22, v2
	v_mov_b32_e32 v23, v2
	v_mov_b32_e32 v24, v2
	v_mov_b32_e32 v25, v2
	v_mov_b32_e32 v34, v2
	v_mov_b32_e32 v35, v2
	v_mov_b32_e32 v36, v2
	v_mov_b32_e32 v37, v2
	v_mov_b32_e32 v38, v2
	v_mov_b32_e32 v39, v2
	v_mov_b32_e32 v40, v2
	v_mov_b32_e32 v41, v2
	v_mov_b32_e32 v50, v2
	v_mov_b32_e32 v51, v2
	v_mov_b32_e32 v52, v2
	v_mov_b32_e32 v53, v2
	v_mov_b32_e32 v54, v2
	v_mov_b32_e32 v55, v2
	v_mov_b32_e32 v56, v2
	v_mov_b32_e32 v57, v2
	v_mov_b32_e32 v10, v2
	v_mov_b32_e32 v11, v2
	v_mov_b32_e32 v12, v2
	v_mov_b32_e32 v13, v2
	v_mov_b32_e32 v14, v2
	v_mov_b32_e32 v15, v2
	v_mov_b32_e32 v16, v2
	v_mov_b32_e32 v17, v2
	v_mov_b32_e32 v26, v2
	v_mov_b32_e32 v27, v2
	v_mov_b32_e32 v28, v2
	v_mov_b32_e32 v29, v2
	v_mov_b32_e32 v30, v2
	v_mov_b32_e32 v31, v2
	v_mov_b32_e32 v32, v2
	v_mov_b32_e32 v33, v2
	v_mov_b32_e32 v42, v2
	v_mov_b32_e32 v43, v2
	v_mov_b32_e32 v44, v2
	v_mov_b32_e32 v45, v2
	v_mov_b32_e32 v46, v2
	v_mov_b32_e32 v47, v2
	v_mov_b32_e32 v48, v2
	v_mov_b32_e32 v49, v2
	v_mov_b32_e32 v58, v2
	v_mov_b32_e32 v59, v2
	v_mov_b32_e32 v60, v2
	v_mov_b32_e32 v61, v2
	v_mov_b32_e32 v62, v2
	v_mov_b32_e32 v63, v2
	v_mov_b32_e32 v64, v2
	v_mov_b32_e32 v65, v2
	v_mov_b32_e32 v66, v2
	v_mov_b32_e32 v67, v2
	v_mov_b32_e32 v68, v2
	v_mov_b32_e32 v69, v2
	v_mov_b32_e32 v70, v2
	v_mov_b32_e32 v71, v2
	v_mov_b32_e32 v72, v2
	v_mov_b32_e32 v73, v2
	v_mov_b32_e32 v82, v2
	v_mov_b32_e32 v83, v2
	v_mov_b32_e32 v84, v2
	v_mov_b32_e32 v85, v2
	v_mov_b32_e32 v86, v2
	v_mov_b32_e32 v87, v2
	v_mov_b32_e32 v88, v2
	v_mov_b32_e32 v89, v2
	v_mov_b32_e32 v98, v2
	v_mov_b32_e32 v99, v2
	v_mov_b32_e32 v100, v2
	v_mov_b32_e32 v101, v2
	v_mov_b32_e32 v102, v2
	v_mov_b32_e32 v103, v2
	v_mov_b32_e32 v104, v2
	v_mov_b32_e32 v105, v2
	v_mov_b32_e32 v126, v2
	v_mov_b32_e32 v127, v2
	v_mov_b32_e32 v128, v2
	v_mov_b32_e32 v129, v2
	v_mov_b32_e32 v130, v2
	v_mov_b32_e32 v131, v2
	v_mov_b32_e32 v132, v2
	v_mov_b32_e32 v133, v2
	v_mov_b32_e32 v74, v2
	v_mov_b32_e32 v75, v2
	v_mov_b32_e32 v76, v2
	v_mov_b32_e32 v77, v2
	v_mov_b32_e32 v78, v2
	v_mov_b32_e32 v79, v2
	v_mov_b32_e32 v80, v2
	v_mov_b32_e32 v81, v2
	v_mov_b32_e32 v90, v2
	v_mov_b32_e32 v91, v2
	v_mov_b32_e32 v92, v2
	v_mov_b32_e32 v93, v2
	v_mov_b32_e32 v94, v2
	v_mov_b32_e32 v95, v2
	v_mov_b32_e32 v96, v2
	v_mov_b32_e32 v97, v2
	v_mov_b32_e32 v106, v2
	v_mov_b32_e32 v107, v2
	v_mov_b32_e32 v108, v2
	v_mov_b32_e32 v109, v2
	v_mov_b32_e32 v110, v2
	v_mov_b32_e32 v111, v2
	v_mov_b32_e32 v112, v2
	v_mov_b32_e32 v113, v2
	v_mov_b32_e32 v138, v2
	v_mov_b32_e32 v139, v2
	v_mov_b32_e32 v140, v2
	v_mov_b32_e32 v141, v2
	v_mov_b32_e32 v142, v2
	v_mov_b32_e32 v143, v2
	v_mov_b32_e32 v144, v2
	v_mov_b32_e32 v145, v2

; #define PG8_BAR __builtin_amdgcn_s_barrier()
; template <class Epi, class Sched, bool ALIGN_EPI = false, bool SP2 = false>
; __device__ __forceinline__ void gemm_phase(PG8_LAS unsigned char* lds, const Gemm g, const Sched& S, const Epi& E) {
;     ...
;         if constexpr (!Epi::AFTER_DRAIN) { E(acc, cur, wr, wc, fr, fq); S.done(cur); }
;         if (!has_next) break;
; #pragma unroll
;         for (int a = 0; a < 2; ++a)
; #pragma unroll
;             for (int b = 0; b < 2; ++b)
; #pragma unroll
;                 for (int m = 0; m < 4; ++m)
; #pragma unroll
;                     for (int n = 0; n < 2; ++n) acc[a][b][m][n] = (f32x4){0.f, 0.f, 0.f, 0.f};
;         cur = nxt; cA = nA; cB = nB; ++ui;
;         if constexpr (ALIGN_EPI) { if (wr == 1) PG8_BAR; }
.LBB0_1381:
	s_or_b64 exec, exec, s[8:9]
	s_and_b64 vcc, exec, s[6:7]
	s_mov_b64 s[6:7], -1
	s_cbranch_vccnz .LBB0_1348
	s_mov_b32 s101, 0
	s_andn2_b64 vcc, exec, s[4:5]
	s_cbranch_vccnz .LBB0_1347
	s_mov_b32 s101, 1
	s_branch .LBB0_1347
